# in-proj rope epilogue: in-place two-element half-wave swap, two pairs interleaved per cluster, shared sine selects (-489 instructions per rope unit and wave)
# speedup vs baseline: 1.0023x; 1.0007x over previous
;     __device__ __forceinline__ void operator()(const f32x4 (&acc)[2][2][4][2], const Unit& u, int wr, int wc, int fr, int fq) const {
;         if (u.kind <= 1) {
;             bf16_t* dst = u.kind == 0 ? Q : Kb; const float sc = u.kind == 0 ? QSCALE : 1.0f;
;             const int axis = wc & 1, pb = 8 * (fq & 1); const bool upper = fq >= 2; float gmax = 0.f;
; #pragma unroll
;             for (int ai = 0; ai < 2; ++ai)
; #pragma unroll
;                 for (int m = 0; m < 4; ++m) {
;                     const int row = u.pm * BM + ai * HALF + wr * 64 + m * 16 + fr;
;                     const bool lat = row < MLAT; const int t = row & (SEQ - 1); const int pos = axis ? (t & 63) : (t >> 6);
;                     f32x4 c0 = *(const f32x4*)(ropec + pos * 16 + pb), c1 = *(const f32x4*)(ropec + pos * 16 + pb + 4), s0 = *(const f32x4*)(ropes + pos * 16 + pb), s1 = *(const f32x4*)(ropes + pos * 16 + pb + 4);
;                     if (!lat) { c0 = (f32x4){1.f, 1.f, 1.f, 1.f}; c1 = c0; s0 = (f32x4){0.f, 0.f, 0.f, 0.f}; s1 = s0; }
;                     if (!upper) { s0 = -s0; s1 = -s1; }
;                     bf16_t* rowp = dst + (size_t)row * DQK + u.pn * BM + wc * 32 + 8 * fq;
; #pragma unroll
;                     for (int bj = 0; bj < 2; ++bj) { const f32x4 a0 = acc[ai][bj][m][0], a1 = acc[ai][bj][m][1]; f32x4 p0, p1;
; #pragma unroll
;                         for (int i = 0; i < 4; ++i) {
;                             auto r0 = __builtin_amdgcn_permlane32_swap(__float_as_uint(a0[i]), __float_as_uint(a0[i]), false, false); p0[i] = __uint_as_float(upper ? r0[0] : r0[1]);
;                             auto r1 = __builtin_amdgcn_permlane32_swap(__float_as_uint(a1[i]), __float_as_uint(a1[i]), false, false); p1[i] = __uint_as_float(upper ? r1[0] : r1[1]); }
;                         const f32x4 o0 = (a0 * c0 + p0 * s0) * sc, o1 = (a1 * c1 + p1 * s1) * sc;
;                         { float ss = ((o0[0] * o0[0] + o0[1] * o0[1]) + (o0[2] * o0[2] + o0[3] * o0[3])) + ((o1[0] * o1[0] + o1[1] * o1[1]) + (o1[2] * o1[2] + o1[3] * o1[3]));
;                           ss += __shfl_xor(ss, 16); ss += __shfl_xor(ss, 32); gmax = fmaxf(gmax, ss); }
;                         u32x4 w; w.x = cvt_pk_bf16(o0[0], o0[1]); w.y = cvt_pk_bf16(o0[2], o0[3]); w.z = cvt_pk_bf16(o1[0], o1[1]); w.w = cvt_pk_bf16(o1[2], o1[3]);
;                         *(u32x4*)(rowp + bj * HALF) = w; }
.LBB0_676:
	s_or_b64 exec, exec, s[2:3]
	s_waitcnt vmcnt(0)
	v_cndmask_b32_e64 v224, v138, v139, s[0:1]
	v_cndmask_b32_e64 v226, v140, v141, s[0:1]
	v_and_b32_e32 v179, 64, v167
	v_add_u32_e32 v182, 64, v179
	s_cmp_eq_u32 s73, 0
	v_cndmask_b32_e64 v228, v142, v143, s[0:1]
	s_cselect_b64 vcc, -1, 0
	v_xor_b32_e32 v148, 16, v167
	s_and_b64 s[2:3], vcc, exec
	v_cndmask_b32_e32 v178, 1.0, v165, vcc
	v_cmp_lt_i32_e32 vcc, v148, v182
	v_cndmask_b32_e32 v148, v167, v148, vcc
	v_lshlrev_b32_e32 v184, 2, v148
	v_xor_b32_e32 v148, 32, v167
	v_cmp_lt_i32_e32 vcc, v148, v182
	v_cndmask_b32_e32 v148, v167, v148, vcc
	v_lshlrev_b32_e32 v183, 2, v148
	v_cndmask_b32_e64 v230, v136, v137, s[0:1]
	v_permlane32_swap_b32_e32 v126, v127
	v_permlane32_swap_b32_e32 v124, v125
	v_cndmask_b32_e64 v240, v134, v135, s[0:1]
	v_cndmask_b32_e64 v242, v132, v133, s[0:1]
	v_pk_mul_f32 v[244:245], v[126:127], v[228:229] op_sel:[1,0] op_sel_hi:[0,0] neg_lo:[1,0]
	v_pk_mul_f32 v[246:247], v[124:125], v[226:227] op_sel:[1,0] op_sel_hi:[0,0] neg_lo:[1,0]
	v_pk_fma_f32 v[186:187], v[126:127], v[240:241], v[244:245] op_sel_hi:[1,0,1]
	v_pk_fma_f32 v[138:139], v[124:125], v[242:243], v[246:247] op_sel_hi:[1,0,1]
	s_nop 0
	v_permlane32_swap_b32_e32 v186, v187
	v_permlane32_swap_b32_e32 v138, v139
	v_pk_mul_f32 v[194:195], v[178:179], v[186:187] op_sel_hi:[0,1]
	s_cselect_b32 s9, s17, s80
	s_cselect_b32 s8, s16, s79
	v_pk_mul_f32 v[138:139], v[178:179], v[138:139] op_sel_hi:[0,1]
	v_permlane32_swap_b32_e32 v120, v121
	v_permlane32_swap_b32_e32 v122, v123
	v_cndmask_b32_e64 v240, v128, v129, s[0:1]
	v_cndmask_b32_e64 v242, v130, v131, s[0:1]
	v_pk_mul_f32 v[244:245], v[120:121], v[230:231] op_sel:[1,0] op_sel_hi:[0,0] neg_lo:[1,0]
	v_pk_mul_f32 v[246:247], v[122:123], v[224:225] op_sel:[1,0] op_sel_hi:[0,0] neg_lo:[1,0]
	v_pk_fma_f32 v[140:141], v[120:121], v[240:241], v[244:245] op_sel_hi:[1,0,1]
	v_pk_fma_f32 v[186:187], v[122:123], v[242:243], v[246:247] op_sel_hi:[1,0,1]
	s_nop 0
	v_permlane32_swap_b32_e32 v140, v141
	v_permlane32_swap_b32_e32 v186, v187
	v_mov_b64_e32 v[136:137], s[8:9]
	s_lshl_b32 s62, s72, 8
	v_pk_mul_f32 v[192:193], v[178:179], v[186:187] op_sel_hi:[0,1]
	v_pk_mul_f32 v[140:141], v[178:179], v[140:141] op_sel_hi:[0,1]
	v_mul_f32_e32 v179, v139, v139
	v_mul_f32_e32 v185, v195, v195
	v_mad_i64_i32 v[136:137], s[2:3], v197, s20, v[136:137]
	s_ashr_i32 s63, s62, 31
	v_fmac_f32_e32 v179, v138, v138
	v_fmac_f32_e32 v185, v194, v194
	v_lshl_add_u64 v[136:137], s[62:63], 1, v[136:137]
	s_lshl_b32 s28, s34, 1
	v_add_f32_e32 v179, v179, v185
	v_mul_f32_e32 v185, v141, v141
	v_mul_f32_e32 v186, v193, v193
	v_lshl_add_u64 v[136:137], v[136:137], 0, s[28:29]
	v_lshlrev_b32_e32 v148, 1, v152
	v_fmac_f32_e32 v185, v140, v140
	v_fmac_f32_e32 v186, v192, v192
	v_lshl_add_u64 v[136:137], v[136:137], 0, v[148:149]
	v_add_f32_e32 v185, v185, v186
	v_cvt_pk_bf16_f32 v138, v138, v139
	v_cvt_pk_bf16_f32 v139, v194, v195
	v_add_f32_e32 v179, v179, v185
	v_cvt_pk_bf16_f32 v140, v140, v141
	v_cvt_pk_bf16_f32 v141, v192, v193
	global_store_dwordx4 v[136:137], v[138:141], off
	ds_bpermute_b32 v185, v184, v179
	s_waitcnt lgkmcnt(0)
	v_add_f32_e32 v185, v179, v185
	v_permlane32_swap_b32_e32 v94, v95
	v_permlane32_swap_b32_e32 v92, v93
	v_cndmask_b32_e64 v240, v134, v135, s[0:1]
	v_cndmask_b32_e64 v242, v132, v133, s[0:1]
	v_pk_mul_f32 v[244:245], v[94:95], v[228:229] op_sel:[1,0] op_sel_hi:[0,0] neg_lo:[1,0]
	v_pk_mul_f32 v[246:247], v[92:93], v[226:227] op_sel:[1,0] op_sel_hi:[0,0] neg_lo:[1,0]
	v_pk_fma_f32 v[134:135], v[94:95], v[240:241], v[244:245] op_sel_hi:[1,0,1]
	v_pk_fma_f32 v[132:133], v[92:93], v[242:243], v[246:247] op_sel_hi:[1,0,1]
	s_nop 0
	v_permlane32_swap_b32_e32 v134, v135
	v_permlane32_swap_b32_e32 v132, v133
	v_pk_mul_f32 v[134:135], v[178:179], v[134:135] op_sel_hi:[0,1]
	v_pk_mul_f32 v[132:133], v[178:179], v[132:133] op_sel_hi:[0,1]
	v_permlane32_swap_b32_e32 v88, v89
	v_permlane32_swap_b32_e32 v90, v91
	v_cndmask_b32_e64 v240, v128, v129, s[0:1]
	v_cndmask_b32_e64 v242, v130, v131, s[0:1]
	v_pk_mul_f32 v[244:245], v[88:89], v[230:231] op_sel:[1,0] op_sel_hi:[0,0] neg_lo:[1,0]
	v_pk_mul_f32 v[246:247], v[90:91], v[224:225] op_sel:[1,0] op_sel_hi:[0,0] neg_lo:[1,0]
	v_pk_fma_f32 v[128:129], v[88:89], v[240:241], v[244:245] op_sel_hi:[1,0,1]
	v_pk_fma_f32 v[130:131], v[90:91], v[242:243], v[246:247] op_sel_hi:[1,0,1]
	s_nop 0
	v_permlane32_swap_b32_e32 v128, v129
	v_permlane32_swap_b32_e32 v130, v131
	v_or_b32_e32 v180, 16, v197
	v_pk_mul_f32 v[138:139], v[178:179], v[130:131] op_sel_hi:[0,1]
	v_pk_mul_f32 v[130:131], v[178:179], v[128:129] op_sel_hi:[0,1]
	v_mul_f32_e32 v128, v133, v133
	v_mul_f32_e32 v129, v135, v135
	v_fmac_f32_e32 v128, v132, v132
	v_fmac_f32_e32 v129, v134, v134
	v_add_f32_e32 v128, v128, v129
	v_mul_f32_e32 v129, v131, v131
	v_mul_f32_e32 v140, v139, v139
	v_fmac_f32_e32 v129, v130, v130
	v_fmac_f32_e32 v140, v138, v138
	v_add_f32_e32 v129, v129, v140
	v_add_f32_e32 v128, v128, v129
	ds_bpermute_b32 v129, v184, v128
	ds_bpermute_b32 v186, v183, v185
	v_cmp_lt_i32_e32 vcc, s97, v180
	s_waitcnt lgkmcnt(1)
	v_add_f32_e32 v187, v128, v129
	v_cvt_pk_bf16_f32 v128, v132, v133
	v_cvt_pk_bf16_f32 v129, v134, v135
	v_cvt_pk_bf16_f32 v130, v130, v131
	v_cvt_pk_bf16_f32 v131, v138, v139
	global_store_dwordx4 v[136:137], v[128:131], off offset:256
	v_mov_b32_e32 v137, v149
	ds_bpermute_b32 v188, v183, v187
	v_mov_b32_e32 v128, s45
	v_cndmask_b32_e64 v128, v180, v128, s[10:11]
	v_lshlrev_b32_e32 v128, 6, v128
	v_and_b32_e32 v136, 0xfc0, v128
	v_lshl_add_u64 v[132:133], v[168:169], 0, v[136:137]
	v_lshl_add_u64 v[140:141], v[170:171], 0, v[136:137]
	global_load_dwordx4 v[128:131], v[132:133], off offset:16
	s_nop 0
	global_load_dwordx4 v[132:135], v[132:133], off
	s_nop 0
	global_load_dwordx4 v[136:139], v[140:141], off offset:16
	s_nop 0
	global_load_dwordx4 v[140:143], v[140:141], off
	s_and_saveexec_b64 s[2:3], vcc
	s_cbranch_execz .LBB0_678
	s_waitcnt vmcnt(3)
	v_mov_b32_e32 v128, 1.0
	s_waitcnt vmcnt(1)
	v_mov_b32_e32 v136, 0
	v_mov_b32_e32 v137, v136
	v_mov_b32_e32 v138, v136
	v_mov_b32_e32 v139, v136
	s_waitcnt vmcnt(0)
	v_mov_b32_e32 v140, v136
	v_mov_b32_e32 v141, v136
	v_mov_b32_e32 v142, v136
	v_mov_b32_e32 v143, v136
	v_mov_b32_e32 v129, v128
	v_mov_b32_e32 v130, v128
	v_mov_b32_e32 v131, v128
	v_mov_b32_e32 v132, v128
	v_mov_b32_e32 v133, v128
	v_mov_b32_e32 v134, v128
	v_mov_b32_e32 v135, v128
; __device__ __forceinline__ unsigned cvt_pk_bf16(float lo, float hi) { unsigned r; asm volatile("v_cvt_pk_bf16_f32 %0, %1, %2" : "=v"(r) : "v"(lo), "v"(hi)); return r; }
;     __device__ __forceinline__ void operator()(const f32x4 (&acc)[2][2][4][2], const Unit& u, int wr, int wc, int fr, int fq) const {
;     ...
;             for (int ai = 0; ai < 2; ++ai)
; #pragma unroll
;                 for (int m = 0; m < 4; ++m) {
;                     const int row = u.pm * BM + ai * HALF + wr * 64 + m * 16 + fr;
;                     const bool lat = row < MLAT; const int t = row & (SEQ - 1); const int pos = axis ? (t & 63) : (t >> 6);
;                     f32x4 c0 = *(const f32x4*)(ropec + pos * 16 + pb), c1 = *(const f32x4*)(ropec + pos * 16 + pb + 4), s0 = *(const f32x4*)(ropes + pos * 16 + pb), s1 = *(const f32x4*)(ropes + pos * 16 + pb + 4);
;                     if (!lat) { c0 = (f32x4){1.f, 1.f, 1.f, 1.f}; c1 = c0; s0 = (f32x4){0.f, 0.f, 0.f, 0.f}; s1 = s0; }
;                     if (!upper) { s0 = -s0; s1 = -s1; }
;                     bf16_t* rowp = dst + (size_t)row * DQK + u.pn * BM + wc * 32 + 8 * fq;
; #pragma unroll
;                     for (int bj = 0; bj < 2; ++bj) { const f32x4 a0 = acc[ai][bj][m][0], a1 = acc[ai][bj][m][1]; f32x4 p0, p1;
; #pragma unroll
;                         for (int i = 0; i < 4; ++i) {
;                             auto r0 = __builtin_amdgcn_permlane32_swap(__float_as_uint(a0[i]), __float_as_uint(a0[i]), false, false); p0[i] = __uint_as_float(upper ? r0[0] : r0[1]);
;                             auto r1 = __builtin_amdgcn_permlane32_swap(__float_as_uint(a1[i]), __float_as_uint(a1[i]), false, false); p1[i] = __uint_as_float(upper ? r1[0] : r1[1]); }
;                         const f32x4 o0 = (a0 * c0 + p0 * s0) * sc, o1 = (a1 * c1 + p1 * s1) * sc;
;                         { float ss = ((o0[0] * o0[0] + o0[1] * o0[1]) + (o0[2] * o0[2] + o0[3] * o0[3])) + ((o1[0] * o1[0] + o1[1] * o1[1]) + (o1[2] * o1[2] + o1[3] * o1[3]));
;                           ss += __shfl_xor(ss, 16); ss += __shfl_xor(ss, 32); gmax = fmaxf(gmax, ss); }
;                         u32x4 w; w.x = cvt_pk_bf16(o0[0], o0[1]); w.y = cvt_pk_bf16(o0[2], o0[3]); w.z = cvt_pk_bf16(o1[0], o1[1]); w.w = cvt_pk_bf16(o1[2], o1[3]);
;                         *(u32x4*)(rowp + bj * HALF) = w; }
;                 }
.LBB0_678:
	s_or_b64 exec, exec, s[2:3]
	s_waitcnt vmcnt(1)
	v_cndmask_b32_e64 v224, v138, v139, s[0:1]
	s_waitcnt vmcnt(0)
	v_cndmask_b32_e64 v226, v140, v141, s[0:1]
	v_cndmask_b32_e64 v228, v136, v137, s[0:1]
	v_mov_b64_e32 v[136:137], s[8:9]
	v_mad_i64_i32 v[136:137], s[2:3], v180, s20, v[136:137]
	v_cndmask_b32_e64 v230, v142, v143, s[0:1]
	v_mov_b32_e32 v179, v178
	v_permlane32_swap_b32_e32 v116, v117
	v_permlane32_swap_b32_e32 v118, v119
	v_cndmask_b32_e64 v240, v132, v133, s[0:1]
	v_cndmask_b32_e64 v242, v134, v135, s[0:1]
	v_pk_mul_f32 v[244:245], v[116:117], v[226:227] op_sel:[1,0] op_sel_hi:[0,0] neg_lo:[1,0]
	v_pk_mul_f32 v[246:247], v[118:119], v[230:231] op_sel:[1,0] op_sel_hi:[0,0] neg_lo:[1,0]
	v_pk_fma_f32 v[138:139], v[116:117], v[240:241], v[244:245] op_sel_hi:[1,0,1]
	v_pk_fma_f32 v[202:203], v[118:119], v[242:243], v[246:247] op_sel_hi:[1,0,1]
	s_nop 0
	v_permlane32_swap_b32_e32 v138, v139
	v_permlane32_swap_b32_e32 v202, v203
	v_mov_b32_e32 v180, v178
	v_mov_b32_e32 v181, v178
	v_pk_mul_f32 v[202:203], v[180:181], v[202:203]
	v_pk_mul_f32 v[138:139], v[178:179], v[138:139]
	v_permlane32_swap_b32_e32 v114, v115
	v_cndmask_b32_e64 v240, v130, v131, s[0:1]
	v_pk_mul_f32 v[244:245], v[114:115], v[224:225] op_sel:[1,0] op_sel_hi:[0,0] neg_lo:[1,0]
	v_pk_fma_f32 v[190:191], v[114:115], v[240:241], v[244:245] op_sel_hi:[1,0,1]
	s_nop 1
	v_permlane32_swap_b32_e32 v190, v191
	v_lshl_add_u64 v[136:137], s[62:63], 1, v[136:137]
	v_permlane32_swap_b32_e32 v112, v113
	v_cndmask_b32_e64 v240, v128, v129, s[0:1]
	v_pk_mul_f32 v[244:245], v[112:113], v[228:229] op_sel:[1,0] op_sel_hi:[0,0] neg_lo:[1,0]
	v_pk_fma_f32 v[140:141], v[112:113], v[240:241], v[244:245] op_sel_hi:[1,0,1]
	s_nop 1
	v_permlane32_swap_b32_e32 v140, v141
	v_pk_mul_f32 v[204:205], v[180:181], v[190:191]
	v_mul_f32_e32 v189, v139, v139
	v_mul_f32_e32 v190, v203, v203
	v_lshl_add_u64 v[136:137], v[136:137], 0, s[28:29]
	v_pk_mul_f32 v[140:141], v[178:179], v[140:141]
	v_fmac_f32_e32 v189, v138, v138
	v_fmac_f32_e32 v190, v202, v202
	v_lshl_add_u64 v[136:137], v[136:137], 0, v[148:149]
	v_add_f32_e32 v189, v189, v190
	v_mul_f32_e32 v190, v141, v141
	v_cvt_pk_bf16_f32 v138, v138, v139
	v_cvt_pk_bf16_f32 v139, v202, v203
	v_fmac_f32_e32 v190, v140, v140
	v_cvt_pk_bf16_f32 v140, v140, v141
	v_cvt_pk_bf16_f32 v141, v204, v205
	global_store_dwordx4 v[136:137], v[138:141], off
	v_mul_f32_e32 v191, v205, v205
	v_fmac_f32_e32 v191, v204, v204
	v_add_f32_e32 v190, v190, v191
	v_permlane32_swap_b32_e32 v86, v87
	v_permlane32_swap_b32_e32 v84, v85
	v_cndmask_b32_e64 v240, v134, v135, s[0:1]
	v_cndmask_b32_e64 v242, v132, v133, s[0:1]
	v_pk_mul_f32 v[244:245], v[86:87], v[230:231] op_sel:[1,0] op_sel_hi:[0,0] neg_lo:[1,0]
	v_pk_mul_f32 v[246:247], v[84:85], v[226:227] op_sel:[1,0] op_sel_hi:[0,0] neg_lo:[1,0]
	v_pk_fma_f32 v[134:135], v[86:87], v[240:241], v[244:245] op_sel_hi:[1,0,1]
	v_pk_fma_f32 v[132:133], v[84:85], v[242:243], v[246:247] op_sel_hi:[1,0,1]
	s_nop 0
	v_permlane32_swap_b32_e32 v134, v135
	v_permlane32_swap_b32_e32 v132, v133
	v_pk_mul_f32 v[134:135], v[180:181], v[134:135]
	v_pk_mul_f32 v[132:133], v[178:179], v[132:133]
	v_permlane32_swap_b32_e32 v80, v81
	v_permlane32_swap_b32_e32 v82, v83
	v_cndmask_b32_e64 v240, v128, v129, s[0:1]
	v_cndmask_b32_e64 v242, v130, v131, s[0:1]
	v_pk_mul_f32 v[244:245], v[80:81], v[228:229] op_sel:[1,0] op_sel_hi:[0,0] neg_lo:[1,0]
	v_pk_mul_f32 v[246:247], v[82:83], v[224:225] op_sel:[1,0] op_sel_hi:[0,0] neg_lo:[1,0]
	v_pk_fma_f32 v[128:129], v[80:81], v[240:241], v[244:245] op_sel_hi:[1,0,1]
	v_pk_fma_f32 v[130:131], v[82:83], v[242:243], v[246:247] op_sel_hi:[1,0,1]
	s_nop 0
	v_permlane32_swap_b32_e32 v128, v129
	v_permlane32_swap_b32_e32 v130, v131
	v_or_b32_e32 v193, 32, v197
	v_pk_mul_f32 v[138:139], v[180:181], v[130:131]
	v_pk_mul_f32 v[130:131], v[178:179], v[128:129]
	v_mul_f32_e32 v128, v133, v133
	v_mul_f32_e32 v129, v135, v135
	v_fmac_f32_e32 v128, v132, v132
	v_fmac_f32_e32 v129, v134, v134
	v_add_f32_e32 v128, v128, v129
	v_mul_f32_e32 v129, v131, v131
	v_mul_f32_e32 v140, v139, v139
	v_fmac_f32_e32 v129, v130, v130
	v_fmac_f32_e32 v140, v138, v138
	v_add_f32_e32 v129, v129, v140
	v_add_f32_e32 v128, v128, v129
	ds_bpermute_b32 v129, v184, v128
	v_add_f32_e32 v189, v189, v190
	ds_bpermute_b32 v190, v184, v189
	v_cmp_lt_i32_e32 vcc, s97, v193
	s_waitcnt lgkmcnt(1)
	v_add_f32_e32 v191, v128, v129
	v_cvt_pk_bf16_f32 v128, v132, v133
	v_cvt_pk_bf16_f32 v129, v134, v135
	v_cvt_pk_bf16_f32 v130, v130, v131
	v_cvt_pk_bf16_f32 v131, v138, v139
	global_store_dwordx4 v[136:137], v[128:131], off offset:256
	v_mov_b32_e32 v137, v149
	s_waitcnt lgkmcnt(0)
	v_add_f32_e32 v189, v189, v190
	v_mov_b32_e32 v128, s45
	v_cndmask_b32_e64 v128, v193, v128, s[10:11]
	v_lshlrev_b32_e32 v128, 6, v128
	v_and_b32_e32 v136, 0xfc0, v128
	v_lshl_add_u64 v[132:133], v[168:169], 0, v[136:137]
	v_lshl_add_u64 v[140:141], v[170:171], 0, v[136:137]
	global_load_dwordx4 v[128:131], v[132:133], off offset:16
	s_nop 0
	global_load_dwordx4 v[132:135], v[132:133], off
	s_nop 0
	global_load_dwordx4 v[136:139], v[140:141], off offset:16
	s_nop 0
	global_load_dwordx4 v[140:143], v[140:141], off
	ds_bpermute_b32 v190, v183, v189
	ds_bpermute_b32 v192, v183, v191
	s_and_saveexec_b64 s[2:3], vcc
	s_cbranch_execz .LBB0_680
	s_waitcnt vmcnt(3)
	v_mov_b32_e32 v128, 1.0
	s_waitcnt vmcnt(1)
	v_mov_b32_e32 v136, 0
	v_mov_b32_e32 v137, v136
	v_mov_b32_e32 v138, v136
	v_mov_b32_e32 v139, v136
	s_waitcnt vmcnt(0)
	v_mov_b32_e32 v140, v136
	v_mov_b32_e32 v141, v136
	v_mov_b32_e32 v142, v136
	v_mov_b32_e32 v143, v136
	v_mov_b32_e32 v129, v128
	v_mov_b32_e32 v130, v128
	v_mov_b32_e32 v131, v128
	v_mov_b32_e32 v132, v128
	v_mov_b32_e32 v133, v128
	v_mov_b32_e32 v134, v128
	v_mov_b32_e32 v135, v128
; __device__ __forceinline__ unsigned cvt_pk_bf16(float lo, float hi) { unsigned r; asm volatile("v_cvt_pk_bf16_f32 %0, %1, %2" : "=v"(r) : "v"(lo), "v"(hi)); return r; }
;     __device__ __forceinline__ void operator()(const f32x4 (&acc)[2][2][4][2], const Unit& u, int wr, int wc, int fr, int fq) const {
;     ...
;             for (int ai = 0; ai < 2; ++ai)
; #pragma unroll
;                 for (int m = 0; m < 4; ++m) {
;                     const int row = u.pm * BM + ai * HALF + wr * 64 + m * 16 + fr;
;                     const bool lat = row < MLAT; const int t = row & (SEQ - 1); const int pos = axis ? (t & 63) : (t >> 6);
;                     f32x4 c0 = *(const f32x4*)(ropec + pos * 16 + pb), c1 = *(const f32x4*)(ropec + pos * 16 + pb + 4), s0 = *(const f32x4*)(ropes + pos * 16 + pb), s1 = *(const f32x4*)(ropes + pos * 16 + pb + 4);
;                     if (!lat) { c0 = (f32x4){1.f, 1.f, 1.f, 1.f}; c1 = c0; s0 = (f32x4){0.f, 0.f, 0.f, 0.f}; s1 = s0; }
;                     if (!upper) { s0 = -s0; s1 = -s1; }
;                     bf16_t* rowp = dst + (size_t)row * DQK + u.pn * BM + wc * 32 + 8 * fq;
; #pragma unroll
;                     for (int bj = 0; bj < 2; ++bj) { const f32x4 a0 = acc[ai][bj][m][0], a1 = acc[ai][bj][m][1]; f32x4 p0, p1;
; #pragma unroll
;                         for (int i = 0; i < 4; ++i) {
;                             auto r0 = __builtin_amdgcn_permlane32_swap(__float_as_uint(a0[i]), __float_as_uint(a0[i]), false, false); p0[i] = __uint_as_float(upper ? r0[0] : r0[1]);
;                             auto r1 = __builtin_amdgcn_permlane32_swap(__float_as_uint(a1[i]), __float_as_uint(a1[i]), false, false); p1[i] = __uint_as_float(upper ? r1[0] : r1[1]); }
;                         const f32x4 o0 = (a0 * c0 + p0 * s0) * sc, o1 = (a1 * c1 + p1 * s1) * sc;
;                         { float ss = ((o0[0] * o0[0] + o0[1] * o0[1]) + (o0[2] * o0[2] + o0[3] * o0[3])) + ((o1[0] * o1[0] + o1[1] * o1[1]) + (o1[2] * o1[2] + o1[3] * o1[3]));
;                           ss += __shfl_xor(ss, 16); ss += __shfl_xor(ss, 32); gmax = fmaxf(gmax, ss); }
;                         u32x4 w; w.x = cvt_pk_bf16(o0[0], o0[1]); w.y = cvt_pk_bf16(o0[2], o0[3]); w.z = cvt_pk_bf16(o1[0], o1[1]); w.w = cvt_pk_bf16(o1[2], o1[3]);
;                         *(u32x4*)(rowp + bj * HALF) = w; }
;                 }
.LBB0_680:
	s_or_b64 exec, exec, s[2:3]
	s_waitcnt vmcnt(1)
	v_cndmask_b32_e64 v224, v138, v139, s[0:1]
	s_waitcnt vmcnt(0)
	v_cndmask_b32_e64 v226, v140, v141, s[0:1]
	v_cndmask_b32_e64 v228, v136, v137, s[0:1]
	v_mov_b64_e32 v[136:137], s[8:9]
	v_mad_i64_i32 v[136:137], s[2:3], v193, s20, v[136:137]
	v_cndmask_b32_e64 v230, v142, v143, s[0:1]
	v_permlane32_swap_b32_e32 v110, v111
	v_permlane32_swap_b32_e32 v108, v109
	v_cndmask_b32_e64 v240, v134, v135, s[0:1]
	v_cndmask_b32_e64 v242, v132, v133, s[0:1]
	v_pk_mul_f32 v[244:245], v[110:111], v[230:231] op_sel:[1,0] op_sel_hi:[0,0] neg_lo:[1,0]
	v_pk_mul_f32 v[246:247], v[108:109], v[226:227] op_sel:[1,0] op_sel_hi:[0,0] neg_lo:[1,0]
	v_pk_fma_f32 v[194:195], v[110:111], v[240:241], v[244:245] op_sel_hi:[1,0,1]
	v_pk_fma_f32 v[138:139], v[108:109], v[242:243], v[246:247] op_sel_hi:[1,0,1]
	s_nop 0
	v_permlane32_swap_b32_e32 v194, v195
	v_permlane32_swap_b32_e32 v138, v139
	v_pk_mul_f32 v[208:209], v[180:181], v[194:195]
	v_pk_mul_f32 v[138:139], v[178:179], v[138:139]
	v_permlane32_swap_b32_e32 v106, v107
	v_cndmask_b32_e64 v240, v130, v131, s[0:1]
	v_pk_mul_f32 v[244:245], v[106:107], v[224:225] op_sel:[1,0] op_sel_hi:[0,0] neg_lo:[1,0]
	v_pk_fma_f32 v[194:195], v[106:107], v[240:241], v[244:245] op_sel_hi:[1,0,1]
	s_nop 1
	v_permlane32_swap_b32_e32 v194, v195
	v_lshl_add_u64 v[136:137], s[62:63], 1, v[136:137]
	v_permlane32_swap_b32_e32 v104, v105
	v_cndmask_b32_e64 v240, v128, v129, s[0:1]
	v_pk_mul_f32 v[244:245], v[104:105], v[228:229] op_sel:[1,0] op_sel_hi:[0,0] neg_lo:[1,0]
	v_pk_fma_f32 v[140:141], v[104:105], v[240:241], v[244:245] op_sel_hi:[1,0,1]
	s_nop 1
	v_permlane32_swap_b32_e32 v140, v141
	v_pk_mul_f32 v[206:207], v[180:181], v[194:195]
	v_mul_f32_e32 v193, v139, v139
	v_mul_f32_e32 v194, v209, v209
	v_lshl_add_u64 v[136:137], v[136:137], 0, s[28:29]
	v_pk_mul_f32 v[140:141], v[178:179], v[140:141]
	v_fmac_f32_e32 v193, v138, v138
	v_fmac_f32_e32 v194, v208, v208
	v_lshl_add_u64 v[136:137], v[136:137], 0, v[148:149]
	v_add_f32_e32 v193, v193, v194
	v_mul_f32_e32 v194, v141, v141
	v_cvt_pk_bf16_f32 v138, v138, v139
	v_cvt_pk_bf16_f32 v139, v208, v209
	v_fmac_f32_e32 v194, v140, v140
	v_cvt_pk_bf16_f32 v140, v140, v141
	v_cvt_pk_bf16_f32 v141, v206, v207
	global_store_dwordx4 v[136:137], v[138:141], off
	v_mul_f32_e32 v195, v207, v207
	v_fmac_f32_e32 v195, v206, v206
	v_add_f32_e32 v194, v194, v195
	v_permlane32_swap_b32_e32 v78, v79
	v_permlane32_swap_b32_e32 v76, v77
	v_cndmask_b32_e64 v240, v134, v135, s[0:1]
	v_cndmask_b32_e64 v242, v132, v133, s[0:1]
	v_pk_mul_f32 v[244:245], v[78:79], v[230:231] op_sel:[1,0] op_sel_hi:[0,0] neg_lo:[1,0]
	v_pk_mul_f32 v[246:247], v[76:77], v[226:227] op_sel:[1,0] op_sel_hi:[0,0] neg_lo:[1,0]
	v_pk_fma_f32 v[134:135], v[78:79], v[240:241], v[244:245] op_sel_hi:[1,0,1]
	v_pk_fma_f32 v[132:133], v[76:77], v[242:243], v[246:247] op_sel_hi:[1,0,1]
	s_nop 0
	v_permlane32_swap_b32_e32 v134, v135
	v_permlane32_swap_b32_e32 v132, v133
	v_pk_mul_f32 v[134:135], v[180:181], v[134:135]
	v_pk_mul_f32 v[132:133], v[178:179], v[132:133]
	v_permlane32_swap_b32_e32 v72, v73
	v_permlane32_swap_b32_e32 v74, v75
	v_cndmask_b32_e64 v240, v128, v129, s[0:1]
	v_cndmask_b32_e64 v242, v130, v131, s[0:1]
	v_pk_mul_f32 v[244:245], v[72:73], v[228:229] op_sel:[1,0] op_sel_hi:[0,0] neg_lo:[1,0]
	v_pk_mul_f32 v[246:247], v[74:75], v[224:225] op_sel:[1,0] op_sel_hi:[0,0] neg_lo:[1,0]
	v_pk_fma_f32 v[128:129], v[72:73], v[240:241], v[244:245] op_sel_hi:[1,0,1]
	v_pk_fma_f32 v[130:131], v[74:75], v[242:243], v[246:247] op_sel_hi:[1,0,1]
	s_nop 0
	v_permlane32_swap_b32_e32 v128, v129
	v_permlane32_swap_b32_e32 v130, v131
	v_add_f32_e32 v193, v193, v194
	v_pk_mul_f32 v[138:139], v[180:181], v[130:131]
	v_pk_mul_f32 v[130:131], v[178:179], v[128:129]
	v_mul_f32_e32 v128, v133, v133
	v_mul_f32_e32 v129, v135, v135
	v_fmac_f32_e32 v128, v132, v132
	v_fmac_f32_e32 v129, v134, v134
	v_add_f32_e32 v128, v128, v129
	v_mul_f32_e32 v129, v131, v131
	v_mul_f32_e32 v140, v139, v139
	v_fmac_f32_e32 v129, v130, v130
	v_fmac_f32_e32 v140, v138, v138
	v_add_f32_e32 v129, v129, v140
	v_add_f32_e32 v128, v128, v129
	ds_bpermute_b32 v129, v184, v128
	v_or_b32_e32 v180, 48, v197
	ds_bpermute_b32 v194, v184, v193
	v_cmp_lt_i32_e32 vcc, s97, v180
	s_waitcnt lgkmcnt(1)
	v_add_f32_e32 v195, v128, v129
	v_cvt_pk_bf16_f32 v128, v132, v133
	v_cvt_pk_bf16_f32 v129, v134, v135
	v_cvt_pk_bf16_f32 v130, v130, v131
	v_cvt_pk_bf16_f32 v131, v138, v139
	global_store_dwordx4 v[136:137], v[128:131], off offset:256
	v_mov_b32_e32 v137, v149
	s_waitcnt lgkmcnt(0)
	v_add_f32_e32 v193, v193, v194
	v_mov_b32_e32 v128, s45
	v_cndmask_b32_e64 v128, v180, v128, s[10:11]
	v_lshlrev_b32_e32 v128, 6, v128
	v_and_b32_e32 v136, 0xfc0, v128
	v_lshl_add_u64 v[132:133], v[168:169], 0, v[136:137]
	v_lshl_add_u64 v[140:141], v[170:171], 0, v[136:137]
	global_load_dwordx4 v[128:131], v[132:133], off offset:16
	s_nop 0
	global_load_dwordx4 v[132:135], v[132:133], off
	s_nop 0
	global_load_dwordx4 v[136:139], v[140:141], off offset:16
	s_nop 0
	global_load_dwordx4 v[140:143], v[140:141], off
	ds_bpermute_b32 v194, v183, v193
	ds_bpermute_b32 v196, v183, v195
	s_and_saveexec_b64 s[2:3], vcc
	s_cbranch_execz .LBB0_682
	s_waitcnt vmcnt(3)
	v_mov_b32_e32 v128, 1.0
	s_waitcnt vmcnt(1)
	v_mov_b32_e32 v136, 0
	v_mov_b32_e32 v137, v136
	v_mov_b32_e32 v138, v136
	v_mov_b32_e32 v139, v136
	s_waitcnt vmcnt(0)
	v_mov_b32_e32 v140, v136
	v_mov_b32_e32 v141, v136
	v_mov_b32_e32 v142, v136
	v_mov_b32_e32 v143, v136
	v_mov_b32_e32 v129, v128
	v_mov_b32_e32 v130, v128
	v_mov_b32_e32 v131, v128
	v_mov_b32_e32 v132, v128
	v_mov_b32_e32 v133, v128
	v_mov_b32_e32 v134, v128
	v_mov_b32_e32 v135, v128
; __device__ __forceinline__ unsigned cvt_pk_bf16(float lo, float hi) { unsigned r; asm volatile("v_cvt_pk_bf16_f32 %0, %1, %2" : "=v"(r) : "v"(lo), "v"(hi)); return r; }
;     __device__ __forceinline__ void operator()(const f32x4 (&acc)[2][2][4][2], const Unit& u, int wr, int wc, int fr, int fq) const {
;     ...
;             for (int ai = 0; ai < 2; ++ai)
; #pragma unroll
;                 for (int m = 0; m < 4; ++m) {
;                     const int row = u.pm * BM + ai * HALF + wr * 64 + m * 16 + fr;
;                     const bool lat = row < MLAT; const int t = row & (SEQ - 1); const int pos = axis ? (t & 63) : (t >> 6);
;                     f32x4 c0 = *(const f32x4*)(ropec + pos * 16 + pb), c1 = *(const f32x4*)(ropec + pos * 16 + pb + 4), s0 = *(const f32x4*)(ropes + pos * 16 + pb), s1 = *(const f32x4*)(ropes + pos * 16 + pb + 4);
;                     if (!lat) { c0 = (f32x4){1.f, 1.f, 1.f, 1.f}; c1 = c0; s0 = (f32x4){0.f, 0.f, 0.f, 0.f}; s1 = s0; }
;                     if (!upper) { s0 = -s0; s1 = -s1; }
;                     bf16_t* rowp = dst + (size_t)row * DQK + u.pn * BM + wc * 32 + 8 * fq;
; #pragma unroll
;                     for (int bj = 0; bj < 2; ++bj) { const f32x4 a0 = acc[ai][bj][m][0], a1 = acc[ai][bj][m][1]; f32x4 p0, p1;
; #pragma unroll
;                         for (int i = 0; i < 4; ++i) {
;                             auto r0 = __builtin_amdgcn_permlane32_swap(__float_as_uint(a0[i]), __float_as_uint(a0[i]), false, false); p0[i] = __uint_as_float(upper ? r0[0] : r0[1]);
;                             auto r1 = __builtin_amdgcn_permlane32_swap(__float_as_uint(a1[i]), __float_as_uint(a1[i]), false, false); p1[i] = __uint_as_float(upper ? r1[0] : r1[1]); }
;                         const f32x4 o0 = (a0 * c0 + p0 * s0) * sc, o1 = (a1 * c1 + p1 * s1) * sc;
;                         { float ss = ((o0[0] * o0[0] + o0[1] * o0[1]) + (o0[2] * o0[2] + o0[3] * o0[3])) + ((o1[0] * o1[0] + o1[1] * o1[1]) + (o1[2] * o1[2] + o1[3] * o1[3]));
;                           ss += __shfl_xor(ss, 16); ss += __shfl_xor(ss, 32); gmax = fmaxf(gmax, ss); }
;                         u32x4 w; w.x = cvt_pk_bf16(o0[0], o0[1]); w.y = cvt_pk_bf16(o0[2], o0[3]); w.z = cvt_pk_bf16(o1[0], o1[1]); w.w = cvt_pk_bf16(o1[2], o1[3]);
;                         *(u32x4*)(rowp + bj * HALF) = w; }
;                 }
.LBB0_682:
	s_or_b64 exec, exec, s[2:3]
	s_waitcnt vmcnt(1)
	v_cndmask_b32_e64 v224, v136, v137, s[0:1]
	v_mov_b64_e32 v[136:137], s[8:9]
	v_mad_i64_i32 v[136:137], s[2:3], v180, s20, v[136:137]
	v_lshl_add_u64 v[136:137], s[62:63], 1, v[136:137]
	s_waitcnt vmcnt(0)
	v_lshl_add_u64 v[136:137], v[136:137], 0, s[28:29]
	v_cndmask_b32_e64 v226, v140, v141, s[0:1]
	v_lshl_add_u64 v[204:205], v[136:137], 0, v[148:149]
	v_cndmask_b32_e64 v228, v138, v139, s[0:1]
	v_cndmask_b32_e64 v230, v142, v143, s[0:1]
	v_permlane32_swap_b32_e32 v100, v101
	v_cndmask_b32_e64 v240, v132, v133, s[0:1]
	v_pk_mul_f32 v[244:245], v[100:101], v[226:227] op_sel:[1,0] op_sel_hi:[0,0] neg_lo:[1,0]
	v_pk_fma_f32 v[136:137], v[100:101], v[240:241], v[244:245] op_sel_hi:[1,0,1]
	s_nop 1
	v_permlane32_swap_b32_e32 v136, v137
	v_pk_mul_f32 v[210:211], v[178:179], v[136:137]
	v_permlane32_swap_b32_e32 v102, v103
	v_cndmask_b32_e64 v240, v134, v135, s[0:1]
	v_pk_mul_f32 v[244:245], v[102:103], v[230:231] op_sel:[1,0] op_sel_hi:[0,0] neg_lo:[1,0]
	v_pk_fma_f32 v[208:209], v[102:103], v[240:241], v[244:245] op_sel_hi:[1,0,1]
	s_nop 1
	v_permlane32_swap_b32_e32 v208, v209
	v_mov_b32_e32 v180, v178
	v_mov_b32_e32 v181, v178
	v_permlane32_swap_b32_e32 v98, v99
	v_cndmask_b32_e64 v240, v130, v131, s[0:1]
	v_pk_mul_f32 v[244:245], v[98:99], v[228:229] op_sel:[1,0] op_sel_hi:[0,0] neg_lo:[1,0]
	v_pk_fma_f32 v[136:137], v[98:99], v[240:241], v[244:245] op_sel_hi:[1,0,1]
	s_nop 1
	v_permlane32_swap_b32_e32 v136, v137
	v_pk_mul_f32 v[208:209], v[180:181], v[208:209]
	v_permlane32_swap_b32_e32 v96, v97
	v_cndmask_b32_e64 v240, v128, v129, s[0:1]
	v_pk_mul_f32 v[244:245], v[96:97], v[224:225] op_sel:[1,0] op_sel_hi:[0,0] neg_lo:[1,0]
	v_pk_fma_f32 v[138:139], v[96:97], v[240:241], v[244:245] op_sel_hi:[1,0,1]
	s_nop 1
	v_permlane32_swap_b32_e32 v138, v139
	v_pk_mul_f32 v[206:207], v[180:181], v[136:137]
	v_cvt_pk_bf16_f32 v136, v210, v211
	v_cvt_pk_bf16_f32 v137, v208, v209
	v_pk_mul_f32 v[212:213], v[178:179], v[138:139]
	v_cvt_pk_bf16_f32 v138, v212, v213
	v_cvt_pk_bf16_f32 v139, v206, v207
	global_store_dwordx4 v[204:205], v[136:139], off
	s_addk_i32 s44, 0x80
	v_permlane32_swap_b32_e32 v70, v71
	v_permlane32_swap_b32_e32 v68, v69
	v_cndmask_b32_e64 v240, v134, v135, s[0:1]
	v_cndmask_b32_e64 v242, v132, v133, s[0:1]
	v_pk_mul_f32 v[244:245], v[70:71], v[230:231] op_sel:[1,0] op_sel_hi:[0,0] neg_lo:[1,0]
	v_pk_mul_f32 v[246:247], v[68:69], v[226:227] op_sel:[1,0] op_sel_hi:[0,0] neg_lo:[1,0]
	v_pk_fma_f32 v[134:135], v[70:71], v[240:241], v[244:245] op_sel_hi:[1,0,1]
	v_pk_fma_f32 v[132:133], v[68:69], v[242:243], v[246:247] op_sel_hi:[1,0,1]
	s_nop 0
	v_permlane32_swap_b32_e32 v134, v135
	v_permlane32_swap_b32_e32 v132, v133
	v_pk_mul_f32 v[214:215], v[180:181], v[134:135]
	v_pk_mul_f32 v[218:219], v[178:179], v[132:133]
	v_permlane32_swap_b32_e32 v64, v65
	v_permlane32_swap_b32_e32 v66, v67
	v_cndmask_b32_e64 v240, v128, v129, s[0:1]
	v_cndmask_b32_e64 v242, v130, v131, s[0:1]
	v_pk_mul_f32 v[244:245], v[64:65], v[224:225] op_sel:[1,0] op_sel_hi:[0,0] neg_lo:[1,0]
	v_pk_mul_f32 v[246:247], v[66:67], v[228:229] op_sel:[1,0] op_sel_hi:[0,0] neg_lo:[1,0]
	v_pk_fma_f32 v[128:129], v[64:65], v[240:241], v[244:245] op_sel_hi:[1,0,1]
	v_pk_fma_f32 v[130:131], v[66:67], v[242:243], v[246:247] op_sel_hi:[1,0,1]
	s_nop 0
	v_permlane32_swap_b32_e32 v128, v129
	v_permlane32_swap_b32_e32 v130, v131
	v_pk_mul_f32 v[216:217], v[178:179], v[128:129]
	v_cvt_pk_bf16_f32 v128, v218, v219
	v_or_b32_e32 v202, s44, v159
	s_lshr_b32 s44, s44, 6
	v_pk_mul_f32 v[198:199], v[180:181], v[130:131]
	v_cvt_pk_bf16_f32 v129, v214, v215
	v_cvt_pk_bf16_f32 v130, v216, v217
	v_mov_b32_e32 v137, v149
	v_cvt_pk_bf16_f32 v131, v198, v199
	global_store_dwordx4 v[204:205], v[128:131], off offset:256
	v_mul_f32_e32 v197, v211, v211
	v_mul_f32_e32 v201, v209, v209
	v_mov_b32_e32 v128, s44
	v_cndmask_b32_e64 v128, v202, v128, s[10:11]
	v_lshlrev_b32_e32 v128, 6, v128
	v_and_b32_e32 v136, 0xfc0, v128
	v_lshl_add_u64 v[132:133], v[168:169], 0, v[136:137]
	v_lshl_add_u64 v[140:141], v[170:171], 0, v[136:137]
	global_load_dwordx4 v[128:131], v[132:133], off offset:16
	s_nop 0
	global_load_dwordx4 v[132:135], v[132:133], off
	s_nop 0
	global_load_dwordx4 v[136:139], v[140:141], off offset:16
	s_nop 0
	global_load_dwordx4 v[140:143], v[140:141], off
	v_fmac_f32_e32 v197, v210, v210
	v_fmac_f32_e32 v201, v208, v208
	v_add_f32_e32 v197, v197, v201
	v_mul_f32_e32 v201, v213, v213
	v_mul_f32_e32 v203, v207, v207
	v_fmac_f32_e32 v201, v212, v212
	v_fmac_f32_e32 v203, v206, v206
	v_add_f32_e32 v201, v201, v203
	v_mul_f32_e32 v203, v219, v219
	v_mul_f32_e32 v204, v215, v215
	v_fmac_f32_e32 v203, v218, v218
	v_fmac_f32_e32 v204, v214, v214
	v_add_f32_e32 v203, v203, v204
	v_mul_f32_e32 v204, v217, v217
	v_mul_f32_e32 v199, v199, v199
	v_fmac_f32_e32 v204, v216, v216
	v_fmac_f32_e32 v199, v198, v198
	v_add_f32_e32 v198, v204, v199
	v_add_f32_e32 v197, v197, v201
	v_add_f32_e32 v199, v203, v198
	ds_bpermute_b32 v201, v184, v197
	ds_bpermute_b32 v203, v184, v199
	v_cmp_lt_i32_e32 vcc, s97, v202
	s_waitcnt lgkmcnt(1)
	v_add_f32_e32 v197, v197, v201
	s_waitcnt lgkmcnt(0)
	v_add_f32_e32 v199, v199, v203
	ds_bpermute_b32 v198, v183, v197
	ds_bpermute_b32 v201, v183, v199
	s_and_saveexec_b64 s[2:3], vcc
	s_cbranch_execz .LBB0_684
	s_waitcnt vmcnt(3)
	v_mov_b32_e32 v128, 1.0
	s_waitcnt vmcnt(1)
	v_mov_b32_e32 v136, 0
	v_mov_b32_e32 v137, v136
	v_mov_b32_e32 v138, v136
	v_mov_b32_e32 v139, v136
	s_waitcnt vmcnt(0)
	v_mov_b32_e32 v140, v136
	v_mov_b32_e32 v141, v136
	v_mov_b32_e32 v142, v136
	v_mov_b32_e32 v143, v136
	v_mov_b32_e32 v129, v128
	v_mov_b32_e32 v130, v128
	v_mov_b32_e32 v131, v128
	v_mov_b32_e32 v132, v128
	v_mov_b32_e32 v133, v128
	v_mov_b32_e32 v134, v128
	v_mov_b32_e32 v135, v128
; __device__ __forceinline__ unsigned cvt_pk_bf16(float lo, float hi) { unsigned r; asm volatile("v_cvt_pk_bf16_f32 %0, %1, %2" : "=v"(r) : "v"(lo), "v"(hi)); return r; }
;     __device__ __forceinline__ void operator()(const f32x4 (&acc)[2][2][4][2], const Unit& u, int wr, int wc, int fr, int fq) const {
;     ...
;             for (int ai = 0; ai < 2; ++ai)
; #pragma unroll
;                 for (int m = 0; m < 4; ++m) {
;                     const int row = u.pm * BM + ai * HALF + wr * 64 + m * 16 + fr;
;                     const bool lat = row < MLAT; const int t = row & (SEQ - 1); const int pos = axis ? (t & 63) : (t >> 6);
;                     f32x4 c0 = *(const f32x4*)(ropec + pos * 16 + pb), c1 = *(const f32x4*)(ropec + pos * 16 + pb + 4), s0 = *(const f32x4*)(ropes + pos * 16 + pb), s1 = *(const f32x4*)(ropes + pos * 16 + pb + 4);
;                     if (!lat) { c0 = (f32x4){1.f, 1.f, 1.f, 1.f}; c1 = c0; s0 = (f32x4){0.f, 0.f, 0.f, 0.f}; s1 = s0; }
;                     if (!upper) { s0 = -s0; s1 = -s1; }
;                     bf16_t* rowp = dst + (size_t)row * DQK + u.pn * BM + wc * 32 + 8 * fq;
; #pragma unroll
;                     for (int bj = 0; bj < 2; ++bj) { const f32x4 a0 = acc[ai][bj][m][0], a1 = acc[ai][bj][m][1]; f32x4 p0, p1;
; #pragma unroll
;                         for (int i = 0; i < 4; ++i) {
;                             auto r0 = __builtin_amdgcn_permlane32_swap(__float_as_uint(a0[i]), __float_as_uint(a0[i]), false, false); p0[i] = __uint_as_float(upper ? r0[0] : r0[1]);
;                             auto r1 = __builtin_amdgcn_permlane32_swap(__float_as_uint(a1[i]), __float_as_uint(a1[i]), false, false); p1[i] = __uint_as_float(upper ? r1[0] : r1[1]); }
;                         const f32x4 o0 = (a0 * c0 + p0 * s0) * sc, o1 = (a1 * c1 + p1 * s1) * sc;
;                         { float ss = ((o0[0] * o0[0] + o0[1] * o0[1]) + (o0[2] * o0[2] + o0[3] * o0[3])) + ((o1[0] * o1[0] + o1[1] * o1[1]) + (o1[2] * o1[2] + o1[3] * o1[3]));
;                           ss += __shfl_xor(ss, 16); ss += __shfl_xor(ss, 32); gmax = fmaxf(gmax, ss); }
;                         u32x4 w; w.x = cvt_pk_bf16(o0[0], o0[1]); w.y = cvt_pk_bf16(o0[2], o0[3]); w.z = cvt_pk_bf16(o1[0], o1[1]); w.w = cvt_pk_bf16(o1[2], o1[3]);
;                         *(u32x4*)(rowp + bj * HALF) = w; }
;                 }
.LBB0_684:
	s_or_b64 exec, exec, s[2:3]
	s_waitcnt vmcnt(1)
	v_cndmask_b32_e64 v224, v138, v139, s[0:1]
	s_waitcnt vmcnt(0)
	v_cndmask_b32_e64 v226, v140, v141, s[0:1]
	v_cndmask_b32_e64 v228, v142, v143, s[0:1]
	v_permlane32_swap_b32_e32 v62, v63
	v_cndmask_b32_e64 v240, v134, v135, s[0:1]
	v_pk_mul_f32 v[244:245], v[62:63], v[228:229] op_sel:[1,0] op_sel_hi:[0,0] neg_lo:[1,0]
	v_pk_fma_f32 v[204:205], v[62:63], v[240:241], v[244:245] op_sel_hi:[1,0,1]
	s_nop 1
	v_permlane32_swap_b32_e32 v204, v205
	v_cndmask_b32_e64 v230, v136, v137, s[0:1]
	v_mov_b64_e32 v[136:137], s[8:9]
	v_permlane32_swap_b32_e32 v60, v61
	v_cndmask_b32_e64 v240, v132, v133, s[0:1]
	v_pk_mul_f32 v[244:245], v[60:61], v[226:227] op_sel:[1,0] op_sel_hi:[0,0] neg_lo:[1,0]
	v_pk_fma_f32 v[138:139], v[60:61], v[240:241], v[244:245] op_sel_hi:[1,0,1]
	s_nop 1
	v_permlane32_swap_b32_e32 v138, v139
	v_pk_mul_f32 v[214:215], v[180:181], v[204:205]
	v_mad_i64_i32 v[136:137], s[2:3], v202, s20, v[136:137]
	v_pk_mul_f32 v[138:139], v[178:179], v[138:139]
	v_permlane32_swap_b32_e32 v58, v59
	v_cndmask_b32_e64 v240, v130, v131, s[0:1]
	v_pk_mul_f32 v[244:245], v[58:59], v[224:225] op_sel:[1,0] op_sel_hi:[0,0] neg_lo:[1,0]
	v_pk_fma_f32 v[204:205], v[58:59], v[240:241], v[244:245] op_sel_hi:[1,0,1]
	s_nop 1
	v_permlane32_swap_b32_e32 v204, v205
	v_lshl_add_u64 v[136:137], s[62:63], 1, v[136:137]
	v_permlane32_swap_b32_e32 v56, v57
	v_cndmask_b32_e64 v240, v128, v129, s[0:1]
	v_pk_mul_f32 v[244:245], v[56:57], v[230:231] op_sel:[1,0] op_sel_hi:[0,0] neg_lo:[1,0]
	v_pk_fma_f32 v[140:141], v[56:57], v[240:241], v[244:245] op_sel_hi:[1,0,1]
	s_nop 1
	v_permlane32_swap_b32_e32 v140, v141
	v_pk_mul_f32 v[212:213], v[180:181], v[204:205]
	v_mul_f32_e32 v203, v139, v139
	v_mul_f32_e32 v204, v215, v215
	v_lshl_add_u64 v[136:137], v[136:137], 0, s[28:29]
	v_pk_mul_f32 v[140:141], v[178:179], v[140:141]
	v_fmac_f32_e32 v203, v138, v138
	v_fmac_f32_e32 v204, v214, v214
	v_lshl_add_u64 v[136:137], v[136:137], 0, v[148:149]
	v_add_f32_e32 v203, v203, v204
	v_mul_f32_e32 v204, v141, v141
	v_cvt_pk_bf16_f32 v138, v138, v139
	v_cvt_pk_bf16_f32 v139, v214, v215
	v_fmac_f32_e32 v204, v140, v140
	v_cvt_pk_bf16_f32 v140, v140, v141
	v_cvt_pk_bf16_f32 v141, v212, v213
	global_store_dwordx4 v[136:137], v[138:141], off
	v_mul_f32_e32 v205, v213, v213
	v_fmac_f32_e32 v205, v212, v212
	v_add_f32_e32 v204, v204, v205
	v_permlane32_swap_b32_e32 v30, v31
	v_permlane32_swap_b32_e32 v28, v29
	v_cndmask_b32_e64 v240, v134, v135, s[0:1]
	v_cndmask_b32_e64 v242, v132, v133, s[0:1]
	v_pk_mul_f32 v[244:245], v[30:31], v[228:229] op_sel:[1,0] op_sel_hi:[0,0] neg_lo:[1,0]
	v_pk_mul_f32 v[246:247], v[28:29], v[226:227] op_sel:[1,0] op_sel_hi:[0,0] neg_lo:[1,0]
	v_pk_fma_f32 v[134:135], v[30:31], v[240:241], v[244:245] op_sel_hi:[1,0,1]
	v_pk_fma_f32 v[132:133], v[28:29], v[242:243], v[246:247] op_sel_hi:[1,0,1]
	s_nop 0
	v_permlane32_swap_b32_e32 v134, v135
	v_permlane32_swap_b32_e32 v132, v133
	v_pk_mul_f32 v[134:135], v[180:181], v[134:135]
	v_pk_mul_f32 v[132:133], v[178:179], v[132:133]
	v_permlane32_swap_b32_e32 v24, v25
	v_permlane32_swap_b32_e32 v26, v27
	v_cndmask_b32_e64 v240, v128, v129, s[0:1]
	v_cndmask_b32_e64 v242, v130, v131, s[0:1]
	v_pk_mul_f32 v[244:245], v[24:25], v[230:231] op_sel:[1,0] op_sel_hi:[0,0] neg_lo:[1,0]
	v_pk_mul_f32 v[246:247], v[26:27], v[224:225] op_sel:[1,0] op_sel_hi:[0,0] neg_lo:[1,0]
	v_pk_fma_f32 v[128:129], v[24:25], v[240:241], v[244:245] op_sel_hi:[1,0,1]
	v_pk_fma_f32 v[130:131], v[26:27], v[242:243], v[246:247] op_sel_hi:[1,0,1]
	s_nop 0
	v_permlane32_swap_b32_e32 v128, v129
	v_permlane32_swap_b32_e32 v130, v131
	v_add_f32_e32 v203, v203, v204
	v_pk_mul_f32 v[138:139], v[180:181], v[130:131]
	v_pk_mul_f32 v[130:131], v[178:179], v[128:129]
	v_mul_f32_e32 v128, v133, v133
	v_mul_f32_e32 v129, v135, v135
	v_fmac_f32_e32 v128, v132, v132
	v_fmac_f32_e32 v129, v134, v134
	v_add_f32_e32 v128, v128, v129
	v_mul_f32_e32 v129, v131, v131
	v_mul_f32_e32 v140, v139, v139
	v_fmac_f32_e32 v129, v130, v130
	v_fmac_f32_e32 v140, v138, v138
	v_add_f32_e32 v129, v129, v140
	v_add_f32_e32 v128, v128, v129
	ds_bpermute_b32 v129, v184, v128
	v_or_b32_e32 v180, 16, v202
	ds_bpermute_b32 v204, v184, v203
	v_cmp_lt_i32_e32 vcc, s97, v180
	s_waitcnt lgkmcnt(1)
	v_add_f32_e32 v205, v128, v129
	v_cvt_pk_bf16_f32 v128, v132, v133
	v_cvt_pk_bf16_f32 v129, v134, v135
	v_cvt_pk_bf16_f32 v130, v130, v131
	v_cvt_pk_bf16_f32 v131, v138, v139
	global_store_dwordx4 v[136:137], v[128:131], off offset:256
	v_mov_b32_e32 v137, v149
	s_waitcnt lgkmcnt(0)
	v_add_f32_e32 v203, v203, v204
	v_mov_b32_e32 v128, s44
	v_cndmask_b32_e64 v128, v180, v128, s[10:11]
	v_lshlrev_b32_e32 v128, 6, v128
	v_and_b32_e32 v136, 0xfc0, v128
	v_lshl_add_u64 v[132:133], v[168:169], 0, v[136:137]
	v_lshl_add_u64 v[140:141], v[170:171], 0, v[136:137]
	global_load_dwordx4 v[128:131], v[132:133], off offset:16
	s_nop 0
	global_load_dwordx4 v[132:135], v[132:133], off
	s_nop 0
	global_load_dwordx4 v[136:139], v[140:141], off offset:16
	s_nop 0
	global_load_dwordx4 v[140:143], v[140:141], off
	ds_bpermute_b32 v204, v183, v203
	ds_bpermute_b32 v206, v183, v205
	s_and_saveexec_b64 s[2:3], vcc
	s_cbranch_execz .LBB0_686
	s_waitcnt vmcnt(3)
	v_mov_b32_e32 v128, 1.0
	s_waitcnt vmcnt(1)
	v_mov_b32_e32 v136, 0
	v_mov_b32_e32 v137, v136
	v_mov_b32_e32 v138, v136
	v_mov_b32_e32 v139, v136
	s_waitcnt vmcnt(0)
	v_mov_b32_e32 v140, v136
	v_mov_b32_e32 v141, v136
	v_mov_b32_e32 v142, v136
	v_mov_b32_e32 v143, v136
	v_mov_b32_e32 v129, v128
	v_mov_b32_e32 v130, v128
	v_mov_b32_e32 v131, v128
	v_mov_b32_e32 v132, v128
	v_mov_b32_e32 v133, v128
	v_mov_b32_e32 v134, v128
	v_mov_b32_e32 v135, v128
; __device__ __forceinline__ unsigned cvt_pk_bf16(float lo, float hi) { unsigned r; asm volatile("v_cvt_pk_bf16_f32 %0, %1, %2" : "=v"(r) : "v"(lo), "v"(hi)); return r; }
;     __device__ __forceinline__ void operator()(const f32x4 (&acc)[2][2][4][2], const Unit& u, int wr, int wc, int fr, int fq) const {
;     ...
;             for (int ai = 0; ai < 2; ++ai)
; #pragma unroll
;                 for (int m = 0; m < 4; ++m) {
;                     const int row = u.pm * BM + ai * HALF + wr * 64 + m * 16 + fr;
;                     const bool lat = row < MLAT; const int t = row & (SEQ - 1); const int pos = axis ? (t & 63) : (t >> 6);
;                     f32x4 c0 = *(const f32x4*)(ropec + pos * 16 + pb), c1 = *(const f32x4*)(ropec + pos * 16 + pb + 4), s0 = *(const f32x4*)(ropes + pos * 16 + pb), s1 = *(const f32x4*)(ropes + pos * 16 + pb + 4);
;                     if (!lat) { c0 = (f32x4){1.f, 1.f, 1.f, 1.f}; c1 = c0; s0 = (f32x4){0.f, 0.f, 0.f, 0.f}; s1 = s0; }
;                     if (!upper) { s0 = -s0; s1 = -s1; }
;                     bf16_t* rowp = dst + (size_t)row * DQK + u.pn * BM + wc * 32 + 8 * fq;
; #pragma unroll
;                     for (int bj = 0; bj < 2; ++bj) { const f32x4 a0 = acc[ai][bj][m][0], a1 = acc[ai][bj][m][1]; f32x4 p0, p1;
; #pragma unroll
;                         for (int i = 0; i < 4; ++i) {
;                             auto r0 = __builtin_amdgcn_permlane32_swap(__float_as_uint(a0[i]), __float_as_uint(a0[i]), false, false); p0[i] = __uint_as_float(upper ? r0[0] : r0[1]);
;                             auto r1 = __builtin_amdgcn_permlane32_swap(__float_as_uint(a1[i]), __float_as_uint(a1[i]), false, false); p1[i] = __uint_as_float(upper ? r1[0] : r1[1]); }
;                         const f32x4 o0 = (a0 * c0 + p0 * s0) * sc, o1 = (a1 * c1 + p1 * s1) * sc;
;                         { float ss = ((o0[0] * o0[0] + o0[1] * o0[1]) + (o0[2] * o0[2] + o0[3] * o0[3])) + ((o1[0] * o1[0] + o1[1] * o1[1]) + (o1[2] * o1[2] + o1[3] * o1[3]));
;                           ss += __shfl_xor(ss, 16); ss += __shfl_xor(ss, 32); gmax = fmaxf(gmax, ss); }
;                         u32x4 w; w.x = cvt_pk_bf16(o0[0], o0[1]); w.y = cvt_pk_bf16(o0[2], o0[3]); w.z = cvt_pk_bf16(o1[0], o1[1]); w.w = cvt_pk_bf16(o1[2], o1[3]);
;                         *(u32x4*)(rowp + bj * HALF) = w; }
;                 }
.LBB0_686:
	s_or_b64 exec, exec, s[2:3]
	s_waitcnt vmcnt(1)
	v_cndmask_b32_e64 v224, v138, v139, s[0:1]
	s_waitcnt vmcnt(0)
	v_cndmask_b32_e64 v226, v140, v141, s[0:1]
	v_cndmask_b32_e64 v228, v136, v137, s[0:1]
	v_mov_b64_e32 v[136:137], s[8:9]
	v_mad_i64_i32 v[136:137], s[2:3], v180, s20, v[136:137]
	v_cndmask_b32_e64 v230, v142, v143, s[0:1]
	v_permlane32_swap_b32_e32 v54, v55
	v_permlane32_swap_b32_e32 v52, v53
	v_cndmask_b32_e64 v240, v134, v135, s[0:1]
	v_cndmask_b32_e64 v242, v132, v133, s[0:1]
	v_pk_mul_f32 v[244:245], v[54:55], v[230:231] op_sel:[1,0] op_sel_hi:[0,0] neg_lo:[1,0]
	v_pk_mul_f32 v[246:247], v[52:53], v[226:227] op_sel:[1,0] op_sel_hi:[0,0] neg_lo:[1,0]
	v_pk_fma_f32 v[216:217], v[54:55], v[240:241], v[244:245] op_sel_hi:[1,0,1]
	v_pk_fma_f32 v[138:139], v[52:53], v[242:243], v[246:247] op_sel_hi:[1,0,1]
	s_nop 0
	v_permlane32_swap_b32_e32 v216, v217
	v_permlane32_swap_b32_e32 v138, v139
	v_mov_b32_e32 v180, v178
	v_mov_b32_e32 v181, v178
	v_pk_mul_f32 v[216:217], v[180:181], v[216:217]
	v_pk_mul_f32 v[138:139], v[178:179], v[138:139]
	v_permlane32_swap_b32_e32 v50, v51
	v_cndmask_b32_e64 v240, v130, v131, s[0:1]
	v_pk_mul_f32 v[244:245], v[50:51], v[224:225] op_sel:[1,0] op_sel_hi:[0,0] neg_lo:[1,0]
	v_pk_fma_f32 v[208:209], v[50:51], v[240:241], v[244:245] op_sel_hi:[1,0,1]
	s_nop 1
	v_permlane32_swap_b32_e32 v208, v209
	v_lshl_add_u64 v[136:137], s[62:63], 1, v[136:137]
	v_permlane32_swap_b32_e32 v48, v49
	v_cndmask_b32_e64 v240, v128, v129, s[0:1]
	v_pk_mul_f32 v[244:245], v[48:49], v[228:229] op_sel:[1,0] op_sel_hi:[0,0] neg_lo:[1,0]
	v_pk_fma_f32 v[140:141], v[48:49], v[240:241], v[244:245] op_sel_hi:[1,0,1]
	s_nop 1
	v_permlane32_swap_b32_e32 v140, v141
	v_pk_mul_f32 v[218:219], v[180:181], v[208:209]
	v_mul_f32_e32 v207, v139, v139
	v_mul_f32_e32 v208, v217, v217
	v_lshl_add_u64 v[136:137], v[136:137], 0, s[28:29]
	v_pk_mul_f32 v[140:141], v[178:179], v[140:141]
	v_fmac_f32_e32 v207, v138, v138
	v_fmac_f32_e32 v208, v216, v216
	v_lshl_add_u64 v[136:137], v[136:137], 0, v[148:149]
	v_add_f32_e32 v207, v207, v208
	v_mul_f32_e32 v208, v141, v141
	v_cvt_pk_bf16_f32 v138, v138, v139
	v_cvt_pk_bf16_f32 v139, v216, v217
	v_fmac_f32_e32 v208, v140, v140
	v_cvt_pk_bf16_f32 v140, v140, v141
	v_cvt_pk_bf16_f32 v141, v218, v219
	global_store_dwordx4 v[136:137], v[138:141], off
	v_mul_f32_e32 v209, v219, v219
	v_fmac_f32_e32 v209, v218, v218
	v_add_f32_e32 v208, v208, v209
	v_permlane32_swap_b32_e32 v22, v23
	v_permlane32_swap_b32_e32 v20, v21
	v_cndmask_b32_e64 v240, v134, v135, s[0:1]
	v_cndmask_b32_e64 v242, v132, v133, s[0:1]
	v_pk_mul_f32 v[244:245], v[22:23], v[230:231] op_sel:[1,0] op_sel_hi:[0,0] neg_lo:[1,0]
	v_pk_mul_f32 v[246:247], v[20:21], v[226:227] op_sel:[1,0] op_sel_hi:[0,0] neg_lo:[1,0]
	v_pk_fma_f32 v[134:135], v[22:23], v[240:241], v[244:245] op_sel_hi:[1,0,1]
	v_pk_fma_f32 v[132:133], v[20:21], v[242:243], v[246:247] op_sel_hi:[1,0,1]
	s_nop 0
	v_permlane32_swap_b32_e32 v134, v135
	v_permlane32_swap_b32_e32 v132, v133
	v_pk_mul_f32 v[134:135], v[180:181], v[134:135]
	v_pk_mul_f32 v[132:133], v[178:179], v[132:133]
	v_permlane32_swap_b32_e32 v16, v17
	v_permlane32_swap_b32_e32 v18, v19
	v_cndmask_b32_e64 v240, v128, v129, s[0:1]
	v_cndmask_b32_e64 v242, v130, v131, s[0:1]
	v_pk_mul_f32 v[244:245], v[16:17], v[228:229] op_sel:[1,0] op_sel_hi:[0,0] neg_lo:[1,0]
	v_pk_mul_f32 v[246:247], v[18:19], v[224:225] op_sel:[1,0] op_sel_hi:[0,0] neg_lo:[1,0]
	v_pk_fma_f32 v[128:129], v[16:17], v[240:241], v[244:245] op_sel_hi:[1,0,1]
	v_pk_fma_f32 v[130:131], v[18:19], v[242:243], v[246:247] op_sel_hi:[1,0,1]
	s_nop 0
	v_permlane32_swap_b32_e32 v128, v129
	v_permlane32_swap_b32_e32 v130, v131
	v_or_b32_e32 v211, 32, v202
	v_pk_mul_f32 v[138:139], v[180:181], v[130:131]
	v_pk_mul_f32 v[130:131], v[178:179], v[128:129]
	v_mul_f32_e32 v128, v133, v133
	v_mul_f32_e32 v129, v135, v135
	v_fmac_f32_e32 v128, v132, v132
	v_fmac_f32_e32 v129, v134, v134
	v_add_f32_e32 v128, v128, v129
	v_mul_f32_e32 v129, v131, v131
	v_mul_f32_e32 v140, v139, v139
	v_fmac_f32_e32 v129, v130, v130
	v_fmac_f32_e32 v140, v138, v138
	v_add_f32_e32 v129, v129, v140
	v_add_f32_e32 v128, v128, v129
	ds_bpermute_b32 v129, v184, v128
	v_add_f32_e32 v207, v207, v208
	ds_bpermute_b32 v208, v184, v207
	v_cmp_lt_i32_e32 vcc, s97, v211
	s_waitcnt lgkmcnt(1)
	v_add_f32_e32 v209, v128, v129
	v_cvt_pk_bf16_f32 v128, v132, v133
	v_cvt_pk_bf16_f32 v129, v134, v135
	v_cvt_pk_bf16_f32 v130, v130, v131
	v_cvt_pk_bf16_f32 v131, v138, v139
	global_store_dwordx4 v[136:137], v[128:131], off offset:256
	v_mov_b32_e32 v137, v149
	s_waitcnt lgkmcnt(0)
	v_add_f32_e32 v207, v207, v208
	v_mov_b32_e32 v128, s44
	v_cndmask_b32_e64 v128, v211, v128, s[10:11]
	v_lshlrev_b32_e32 v128, 6, v128
	v_and_b32_e32 v136, 0xfc0, v128
	v_lshl_add_u64 v[132:133], v[168:169], 0, v[136:137]
	v_lshl_add_u64 v[140:141], v[170:171], 0, v[136:137]
	global_load_dwordx4 v[128:131], v[132:133], off offset:16
	s_nop 0
	global_load_dwordx4 v[132:135], v[132:133], off
	s_nop 0
	global_load_dwordx4 v[136:139], v[140:141], off offset:16
	s_nop 0
	global_load_dwordx4 v[140:143], v[140:141], off
	ds_bpermute_b32 v208, v183, v207
	ds_bpermute_b32 v210, v183, v209
	s_and_saveexec_b64 s[2:3], vcc
	s_cbranch_execz .LBB0_688
	s_waitcnt vmcnt(3)
	v_mov_b32_e32 v128, 1.0
	s_waitcnt vmcnt(1)
	v_mov_b32_e32 v136, 0
	v_mov_b32_e32 v137, v136
	v_mov_b32_e32 v138, v136
	v_mov_b32_e32 v139, v136
	s_waitcnt vmcnt(0)
	v_mov_b32_e32 v140, v136
	v_mov_b32_e32 v141, v136
	v_mov_b32_e32 v142, v136
	v_mov_b32_e32 v143, v136
	v_mov_b32_e32 v129, v128
	v_mov_b32_e32 v130, v128
	v_mov_b32_e32 v131, v128
	v_mov_b32_e32 v132, v128
	v_mov_b32_e32 v133, v128
	v_mov_b32_e32 v134, v128
	v_mov_b32_e32 v135, v128
; __device__ __forceinline__ unsigned cvt_pk_bf16(float lo, float hi) { unsigned r; asm volatile("v_cvt_pk_bf16_f32 %0, %1, %2" : "=v"(r) : "v"(lo), "v"(hi)); return r; }
;     __device__ __forceinline__ void operator()(const f32x4 (&acc)[2][2][4][2], const Unit& u, int wr, int wc, int fr, int fq) const {
;     ...
;             for (int ai = 0; ai < 2; ++ai)
; #pragma unroll
;                 for (int m = 0; m < 4; ++m) {
;                     const int row = u.pm * BM + ai * HALF + wr * 64 + m * 16 + fr;
;                     const bool lat = row < MLAT; const int t = row & (SEQ - 1); const int pos = axis ? (t & 63) : (t >> 6);
;                     f32x4 c0 = *(const f32x4*)(ropec + pos * 16 + pb), c1 = *(const f32x4*)(ropec + pos * 16 + pb + 4), s0 = *(const f32x4*)(ropes + pos * 16 + pb), s1 = *(const f32x4*)(ropes + pos * 16 + pb + 4);
;                     if (!lat) { c0 = (f32x4){1.f, 1.f, 1.f, 1.f}; c1 = c0; s0 = (f32x4){0.f, 0.f, 0.f, 0.f}; s1 = s0; }
;                     if (!upper) { s0 = -s0; s1 = -s1; }
;                     bf16_t* rowp = dst + (size_t)row * DQK + u.pn * BM + wc * 32 + 8 * fq;
; #pragma unroll
;                     for (int bj = 0; bj < 2; ++bj) { const f32x4 a0 = acc[ai][bj][m][0], a1 = acc[ai][bj][m][1]; f32x4 p0, p1;
; #pragma unroll
;                         for (int i = 0; i < 4; ++i) {
;                             auto r0 = __builtin_amdgcn_permlane32_swap(__float_as_uint(a0[i]), __float_as_uint(a0[i]), false, false); p0[i] = __uint_as_float(upper ? r0[0] : r0[1]);
;                             auto r1 = __builtin_amdgcn_permlane32_swap(__float_as_uint(a1[i]), __float_as_uint(a1[i]), false, false); p1[i] = __uint_as_float(upper ? r1[0] : r1[1]); }
;                         const f32x4 o0 = (a0 * c0 + p0 * s0) * sc, o1 = (a1 * c1 + p1 * s1) * sc;
;                         { float ss = ((o0[0] * o0[0] + o0[1] * o0[1]) + (o0[2] * o0[2] + o0[3] * o0[3])) + ((o1[0] * o1[0] + o1[1] * o1[1]) + (o1[2] * o1[2] + o1[3] * o1[3]));
;                           ss += __shfl_xor(ss, 16); ss += __shfl_xor(ss, 32); gmax = fmaxf(gmax, ss); }
;                         u32x4 w; w.x = cvt_pk_bf16(o0[0], o0[1]); w.y = cvt_pk_bf16(o0[2], o0[3]); w.z = cvt_pk_bf16(o1[0], o1[1]); w.w = cvt_pk_bf16(o1[2], o1[3]);
;                         *(u32x4*)(rowp + bj * HALF) = w; }
;                 }
.LBB0_688:
	s_or_b64 exec, exec, s[2:3]
	s_waitcnt vmcnt(1)
	v_cndmask_b32_e64 v224, v138, v139, s[0:1]
	s_waitcnt vmcnt(0)
	v_cndmask_b32_e64 v226, v140, v141, s[0:1]
	v_cndmask_b32_e64 v228, v136, v137, s[0:1]
	v_mov_b64_e32 v[136:137], s[8:9]
	v_mad_i64_i32 v[136:137], s[2:3], v211, s20, v[136:137]
	v_cndmask_b32_e64 v230, v142, v143, s[0:1]
	v_permlane32_swap_b32_e32 v46, v47
	v_permlane32_swap_b32_e32 v44, v45
	v_cndmask_b32_e64 v240, v134, v135, s[0:1]
	v_cndmask_b32_e64 v242, v132, v133, s[0:1]
	v_pk_mul_f32 v[244:245], v[46:47], v[230:231] op_sel:[1,0] op_sel_hi:[0,0] neg_lo:[1,0]
	v_pk_mul_f32 v[246:247], v[44:45], v[226:227] op_sel:[1,0] op_sel_hi:[0,0] neg_lo:[1,0]
	v_pk_fma_f32 v[212:213], v[46:47], v[240:241], v[244:245] op_sel_hi:[1,0,1]
	v_pk_fma_f32 v[138:139], v[44:45], v[242:243], v[246:247] op_sel_hi:[1,0,1]
	s_nop 0
	v_permlane32_swap_b32_e32 v212, v213
	v_permlane32_swap_b32_e32 v138, v139
	v_pk_mul_f32 v[222:223], v[180:181], v[212:213]
	v_pk_mul_f32 v[138:139], v[178:179], v[138:139]
	v_permlane32_swap_b32_e32 v42, v43
	v_cndmask_b32_e64 v240, v130, v131, s[0:1]
	v_pk_mul_f32 v[244:245], v[42:43], v[224:225] op_sel:[1,0] op_sel_hi:[0,0] neg_lo:[1,0]
	v_pk_fma_f32 v[212:213], v[42:43], v[240:241], v[244:245] op_sel_hi:[1,0,1]
	s_nop 1
	v_permlane32_swap_b32_e32 v212, v213
	v_lshl_add_u64 v[136:137], s[62:63], 1, v[136:137]
	v_permlane32_swap_b32_e32 v40, v41
	v_cndmask_b32_e64 v240, v128, v129, s[0:1]
	v_pk_mul_f32 v[244:245], v[40:41], v[228:229] op_sel:[1,0] op_sel_hi:[0,0] neg_lo:[1,0]
	v_pk_fma_f32 v[140:141], v[40:41], v[240:241], v[244:245] op_sel_hi:[1,0,1]
	s_nop 1
	v_permlane32_swap_b32_e32 v140, v141
	v_pk_mul_f32 v[220:221], v[180:181], v[212:213]
	v_mul_f32_e32 v211, v139, v139
	v_mul_f32_e32 v212, v223, v223
	v_lshl_add_u64 v[136:137], v[136:137], 0, s[28:29]
	v_pk_mul_f32 v[140:141], v[178:179], v[140:141]
	v_fmac_f32_e32 v211, v138, v138
	v_fmac_f32_e32 v212, v222, v222
	v_lshl_add_u64 v[136:137], v[136:137], 0, v[148:149]
	v_add_f32_e32 v211, v211, v212
	v_mul_f32_e32 v212, v141, v141
	v_cvt_pk_bf16_f32 v138, v138, v139
	v_cvt_pk_bf16_f32 v139, v222, v223
	v_fmac_f32_e32 v212, v140, v140
	v_cvt_pk_bf16_f32 v140, v140, v141
	v_cvt_pk_bf16_f32 v141, v220, v221
	global_store_dwordx4 v[136:137], v[138:141], off
	v_mul_f32_e32 v213, v221, v221
	v_fmac_f32_e32 v213, v220, v220
	v_add_f32_e32 v212, v212, v213
	v_permlane32_swap_b32_e32 v14, v15
	v_permlane32_swap_b32_e32 v12, v13
	v_cndmask_b32_e64 v240, v134, v135, s[0:1]
	v_cndmask_b32_e64 v242, v132, v133, s[0:1]
	v_pk_mul_f32 v[244:245], v[14:15], v[230:231] op_sel:[1,0] op_sel_hi:[0,0] neg_lo:[1,0]
	v_pk_mul_f32 v[246:247], v[12:13], v[226:227] op_sel:[1,0] op_sel_hi:[0,0] neg_lo:[1,0]
	v_pk_fma_f32 v[134:135], v[14:15], v[240:241], v[244:245] op_sel_hi:[1,0,1]
	v_pk_fma_f32 v[132:133], v[12:13], v[242:243], v[246:247] op_sel_hi:[1,0,1]
	s_nop 0
	v_permlane32_swap_b32_e32 v134, v135
	v_permlane32_swap_b32_e32 v132, v133
	v_pk_mul_f32 v[134:135], v[180:181], v[134:135]
	v_pk_mul_f32 v[132:133], v[178:179], v[132:133]
	v_permlane32_swap_b32_e32 v8, v9
	v_permlane32_swap_b32_e32 v10, v11
	v_cndmask_b32_e64 v240, v128, v129, s[0:1]
	v_cndmask_b32_e64 v242, v130, v131, s[0:1]
	v_pk_mul_f32 v[244:245], v[8:9], v[228:229] op_sel:[1,0] op_sel_hi:[0,0] neg_lo:[1,0]
	v_pk_mul_f32 v[246:247], v[10:11], v[224:225] op_sel:[1,0] op_sel_hi:[0,0] neg_lo:[1,0]
	v_pk_fma_f32 v[128:129], v[8:9], v[240:241], v[244:245] op_sel_hi:[1,0,1]
	v_pk_fma_f32 v[130:131], v[10:11], v[242:243], v[246:247] op_sel_hi:[1,0,1]
	s_nop 0
	v_permlane32_swap_b32_e32 v128, v129
	v_permlane32_swap_b32_e32 v130, v131
	v_or_b32_e32 v202, 48, v202
	v_pk_mul_f32 v[138:139], v[180:181], v[130:131]
	v_pk_mul_f32 v[130:131], v[178:179], v[128:129]
	v_mul_f32_e32 v128, v133, v133
	v_mul_f32_e32 v129, v135, v135
	v_fmac_f32_e32 v128, v132, v132
	v_fmac_f32_e32 v129, v134, v134
	v_add_f32_e32 v128, v128, v129
	v_mul_f32_e32 v129, v131, v131
	v_mul_f32_e32 v140, v139, v139
	v_fmac_f32_e32 v129, v130, v130
	v_fmac_f32_e32 v140, v138, v138
	v_add_f32_e32 v129, v129, v140
	v_add_f32_e32 v128, v128, v129
	ds_bpermute_b32 v129, v184, v128
	v_add_f32_e32 v211, v211, v212
	ds_bpermute_b32 v212, v184, v211
	v_cmp_lt_i32_e32 vcc, s97, v202
	s_waitcnt lgkmcnt(1)
	v_add_f32_e32 v180, v128, v129
	v_cvt_pk_bf16_f32 v128, v132, v133
	v_cvt_pk_bf16_f32 v129, v134, v135
	v_cvt_pk_bf16_f32 v130, v130, v131
	v_cvt_pk_bf16_f32 v131, v138, v139
	global_store_dwordx4 v[136:137], v[128:131], off offset:256
	v_mov_b32_e32 v137, v149
	s_waitcnt lgkmcnt(0)
	v_add_f32_e32 v211, v211, v212
	v_mov_b32_e32 v128, s44
	v_cndmask_b32_e64 v128, v202, v128, s[10:11]
	v_lshlrev_b32_e32 v128, 6, v128
	v_and_b32_e32 v136, 0xfc0, v128
	v_lshl_add_u64 v[132:133], v[168:169], 0, v[136:137]
	v_lshl_add_u64 v[140:141], v[170:171], 0, v[136:137]
	global_load_dwordx4 v[128:131], v[132:133], off offset:16
	s_nop 0
	global_load_dwordx4 v[132:135], v[132:133], off
	s_nop 0
	global_load_dwordx4 v[136:139], v[140:141], off offset:16
	s_nop 0
	global_load_dwordx4 v[140:143], v[140:141], off
	ds_bpermute_b32 v212, v183, v211
	ds_bpermute_b32 v181, v183, v180
	s_and_saveexec_b64 s[2:3], vcc
	s_cbranch_execz .LBB0_690
	s_waitcnt vmcnt(3)
	v_mov_b32_e32 v128, 1.0
	s_waitcnt vmcnt(1)
	v_mov_b32_e32 v136, 0
	v_mov_b32_e32 v137, v136
	v_mov_b32_e32 v138, v136
	v_mov_b32_e32 v139, v136
	s_waitcnt vmcnt(0)
	v_mov_b32_e32 v140, v136
	v_mov_b32_e32 v141, v136
	v_mov_b32_e32 v142, v136
	v_mov_b32_e32 v143, v136
	v_mov_b32_e32 v129, v128
	v_mov_b32_e32 v130, v128
	v_mov_b32_e32 v131, v128
	v_mov_b32_e32 v132, v128
	v_mov_b32_e32 v133, v128
	v_mov_b32_e32 v134, v128
	v_mov_b32_e32 v135, v128
;     __device__ __forceinline__ void operator()(const f32x4 (&acc)[2][2][4][2], const Unit& u, int wr, int wc, int fr, int fq) const {
;     ...
;             for (int ai = 0; ai < 2; ++ai)
; #pragma unroll
;                 for (int m = 0; m < 4; ++m) {
;                     const int row = u.pm * BM + ai * HALF + wr * 64 + m * 16 + fr;
;                     const bool lat = row < MLAT; const int t = row & (SEQ - 1); const int pos = axis ? (t & 63) : (t >> 6);
;                     f32x4 c0 = *(const f32x4*)(ropec + pos * 16 + pb), c1 = *(const f32x4*)(ropec + pos * 16 + pb + 4), s0 = *(const f32x4*)(ropes + pos * 16 + pb), s1 = *(const f32x4*)(ropes + pos * 16 + pb + 4);
;                     if (!lat) { c0 = (f32x4){1.f, 1.f, 1.f, 1.f}; c1 = c0; s0 = (f32x4){0.f, 0.f, 0.f, 0.f}; s1 = s0; }
;                     if (!upper) { s0 = -s0; s1 = -s1; }
;                     bf16_t* rowp = dst + (size_t)row * DQK + u.pn * BM + wc * 32 + 8 * fq;
; #pragma unroll
;                     for (int bj = 0; bj < 2; ++bj) { const f32x4 a0 = acc[ai][bj][m][0], a1 = acc[ai][bj][m][1]; f32x4 p0, p1;
; #pragma unroll
;                         for (int i = 0; i < 4; ++i) {
;                             auto r0 = __builtin_amdgcn_permlane32_swap(__float_as_uint(a0[i]), __float_as_uint(a0[i]), false, false); p0[i] = __uint_as_float(upper ? r0[0] : r0[1]);
;                             auto r1 = __builtin_amdgcn_permlane32_swap(__float_as_uint(a1[i]), __float_as_uint(a1[i]), false, false); p1[i] = __uint_as_float(upper ? r1[0] : r1[1]); }
;                         const f32x4 o0 = (a0 * c0 + p0 * s0) * sc, o1 = (a1 * c1 + p1 * s1) * sc;
;                         { float ss = ((o0[0] * o0[0] + o0[1] * o0[1]) + (o0[2] * o0[2] + o0[3] * o0[3])) + ((o1[0] * o1[0] + o1[1] * o1[1]) + (o1[2] * o1[2] + o1[3] * o1[3]));
;                           ss += __shfl_xor(ss, 16); ss += __shfl_xor(ss, 32); gmax = fmaxf(gmax, ss); }
;                         u32x4 w; w.x = cvt_pk_bf16(o0[0], o0[1]); w.y = cvt_pk_bf16(o0[2], o0[3]); w.z = cvt_pk_bf16(o1[0], o1[1]); w.w = cvt_pk_bf16(o1[2], o1[3]);
;                         *(u32x4*)(rowp + bj * HALF) = w; }
;                 }
; #pragma unroll
;             for (int o = 1; o < 16; o <<= 1) gmax = fmaxf(gmax, __shfl_xor(gmax, o));
;             if ((fr | fq) == 0) atomicMax(nmax + u.kind * 64 + ((u.pm * 8 + wr * 4 + wc) & 63), __float_as_uint(gmax));
.LBB0_690:
	s_or_b64 exec, exec, s[2:3]
	v_add_f32_e32 v185, v185, v186
	v_add_f32_e32 v186, v187, v188
	v_max3_f32 v185, v185, 0, v186
	v_add_f32_e32 v186, v189, v190
	v_add_f32_e32 v187, v191, v192
	v_max3_f32 v185, v185, v186, v187
	v_add_f32_e32 v186, v193, v194
	v_add_f32_e32 v187, v195, v196
	v_max3_f32 v185, v185, v186, v187
	v_add_f32_e32 v186, v197, v198
	v_add_f32_e32 v187, v199, v201
	v_max3_f32 v185, v185, v186, v187
	v_add_f32_e32 v186, v203, v204
	v_add_f32_e32 v187, v205, v206
	v_max3_f32 v185, v185, v186, v187
	v_add_f32_e32 v186, v207, v208
	v_add_f32_e32 v187, v209, v210
	v_max3_f32 v185, v185, v186, v187
	s_waitcnt lgkmcnt(1)
	v_add_f32_e32 v186, v211, v212
	s_waitcnt lgkmcnt(0)
	v_add_f32_e32 v180, v180, v181
	v_max3_f32 v185, v185, v186, v180
	s_waitcnt vmcnt(1)
	v_cndmask_b32_e64 v224, v138, v139, s[0:1]
	s_waitcnt vmcnt(0)
	v_cndmask_b32_e64 v226, v136, v137, s[0:1]
	v_cndmask_b32_e64 v228, v140, v141, s[0:1]
	v_mov_b64_e32 v[136:137], s[8:9]
	v_mad_i64_i32 v[136:137], s[2:3], v202, s20, v[136:137]
	v_lshl_add_u64 v[136:137], s[62:63], 1, v[136:137]
	v_lshl_add_u64 v[136:137], v[136:137], 0, s[28:29]
	v_lshl_add_u64 v[136:137], v[136:137], 0, v[148:149]
	v_cndmask_b32_e64 v230, v142, v143, s[0:1]
	v_permlane32_swap_b32_e32 v36, v37
	v_permlane32_swap_b32_e32 v38, v39
	v_cndmask_b32_e64 v240, v132, v133, s[0:1]
	v_cndmask_b32_e64 v242, v134, v135, s[0:1]
	v_pk_mul_f32 v[244:245], v[36:37], v[228:229] op_sel:[1,0] op_sel_hi:[0,0] neg_lo:[1,0]
	v_pk_mul_f32 v[246:247], v[38:39], v[230:231] op_sel:[1,0] op_sel_hi:[0,0] neg_lo:[1,0]
	v_pk_fma_f32 v[138:139], v[36:37], v[240:241], v[244:245] op_sel_hi:[1,0,1]
	v_pk_fma_f32 v[190:191], v[38:39], v[242:243], v[246:247] op_sel_hi:[1,0,1]
	s_nop 0
	v_permlane32_swap_b32_e32 v138, v139
	v_permlane32_swap_b32_e32 v190, v191
	v_mov_b32_e32 v194, v178
	v_mov_b32_e32 v195, v178
	v_pk_mul_f32 v[190:191], v[194:195], v[190:191]
	v_pk_mul_f32 v[138:139], v[178:179], v[138:139]
	v_permlane32_swap_b32_e32 v34, v35
	v_permlane32_swap_b32_e32 v32, v33
	v_cndmask_b32_e64 v240, v130, v131, s[0:1]
	v_cndmask_b32_e64 v242, v128, v129, s[0:1]
	v_pk_mul_f32 v[244:245], v[34:35], v[224:225] op_sel:[1,0] op_sel_hi:[0,0] neg_lo:[1,0]
	v_pk_mul_f32 v[246:247], v[32:33], v[226:227] op_sel:[1,0] op_sel_hi:[0,0] neg_lo:[1,0]
	v_pk_fma_f32 v[192:193], v[34:35], v[240:241], v[244:245] op_sel_hi:[1,0,1]
	v_pk_fma_f32 v[140:141], v[32:33], v[242:243], v[246:247] op_sel_hi:[1,0,1]
	s_nop 0
	v_permlane32_swap_b32_e32 v192, v193
	v_permlane32_swap_b32_e32 v140, v141
	v_mul_f32_e32 v148, v139, v139
	v_mul_f32_e32 v196, v191, v191
	v_pk_mul_f32 v[192:193], v[194:195], v[192:193]
	v_pk_mul_f32 v[140:141], v[178:179], v[140:141]
	v_fmac_f32_e32 v148, v138, v138
	v_fmac_f32_e32 v196, v190, v190
	v_add_f32_e32 v148, v148, v196
	v_mul_f32_e32 v196, v141, v141
	v_mul_f32_e32 v197, v193, v193
	v_cvt_pk_bf16_f32 v138, v138, v139
	v_cvt_pk_bf16_f32 v139, v190, v191
	v_fmac_f32_e32 v196, v140, v140
	v_fmac_f32_e32 v197, v192, v192
	v_cvt_pk_bf16_f32 v140, v140, v141
	v_cvt_pk_bf16_f32 v141, v192, v193
	global_store_dwordx4 v[136:137], v[138:141], off
	v_add_f32_e32 v196, v196, v197
	v_add_f32_e32 v148, v148, v196
	ds_bpermute_b32 v196, v184, v148
	s_waitcnt lgkmcnt(0)
	v_add_f32_e32 v148, v148, v196
	ds_bpermute_b32 v196, v183, v148
	s_waitcnt lgkmcnt(0)
	v_add_f32_e32 v148, v148, v196
	v_permlane32_swap_b32_e32 v6, v7
	v_permlane32_swap_b32_e32 v4, v5
	v_cndmask_b32_e64 v240, v134, v135, s[0:1]
	v_cndmask_b32_e64 v242, v132, v133, s[0:1]
	v_pk_mul_f32 v[244:245], v[6:7], v[230:231] op_sel:[1,0] op_sel_hi:[0,0] neg_lo:[1,0]
	v_pk_mul_f32 v[246:247], v[4:5], v[228:229] op_sel:[1,0] op_sel_hi:[0,0] neg_lo:[1,0]
	v_pk_fma_f32 v[134:135], v[6:7], v[240:241], v[244:245] op_sel_hi:[1,0,1]
	v_pk_fma_f32 v[132:133], v[4:5], v[242:243], v[246:247] op_sel_hi:[1,0,1]
	s_nop 0
	v_permlane32_swap_b32_e32 v134, v135
	v_permlane32_swap_b32_e32 v132, v133
	v_pk_mul_f32 v[134:135], v[194:195], v[134:135]
	v_pk_mul_f32 v[132:133], v[178:179], v[132:133]
	v_permlane32_swap_b32_e32 v0, v1
	v_permlane32_swap_b32_e32 v2, v3
	v_cndmask_b32_e64 v240, v128, v129, s[0:1]
	v_cndmask_b32_e64 v242, v130, v131, s[0:1]
	v_pk_mul_f32 v[244:245], v[0:1], v[226:227] op_sel:[1,0] op_sel_hi:[0,0] neg_lo:[1,0]
	v_pk_mul_f32 v[246:247], v[2:3], v[224:225] op_sel:[1,0] op_sel_hi:[0,0] neg_lo:[1,0]
	v_pk_fma_f32 v[128:129], v[0:1], v[240:241], v[244:245] op_sel_hi:[1,0,1]
	v_pk_fma_f32 v[130:131], v[2:3], v[242:243], v[246:247] op_sel_hi:[1,0,1]
	s_nop 0
	v_permlane32_swap_b32_e32 v128, v129
	v_permlane32_swap_b32_e32 v130, v131
	s_nop 0
	v_pk_mul_f32 v[138:139], v[194:195], v[130:131]
	v_pk_mul_f32 v[130:131], v[178:179], v[128:129]
	v_mul_f32_e32 v128, v133, v133
	v_mul_f32_e32 v129, v135, v135
	v_fmac_f32_e32 v128, v132, v132
	v_fmac_f32_e32 v129, v134, v134
	v_add_f32_e32 v128, v128, v129
	v_mul_f32_e32 v129, v131, v131
	v_mul_f32_e32 v140, v139, v139
	v_fmac_f32_e32 v129, v130, v130
	v_fmac_f32_e32 v140, v138, v138
	v_add_f32_e32 v129, v129, v140
	v_add_f32_e32 v128, v128, v129
	ds_bpermute_b32 v129, v184, v128
	s_waitcnt lgkmcnt(0)
	v_add_f32_e32 v128, v128, v129
	ds_bpermute_b32 v129, v183, v128
	s_waitcnt lgkmcnt(0)
	v_add_f32_e32 v128, v128, v129
	v_max3_f32 v140, v185, v148, v128
	v_cvt_pk_bf16_f32 v128, v132, v133
	v_cvt_pk_bf16_f32 v129, v134, v135
	v_cvt_pk_bf16_f32 v130, v130, v131
	v_cvt_pk_bf16_f32 v131, v138, v139
	global_store_dwordx4 v[136:137], v[128:131], off offset:256
	s_nop 1
	v_xor_b32_e32 v128, 1, v167
	v_cmp_lt_i32_e32 vcc, v128, v182
	v_xor_b32_e32 v129, 2, v167
	s_nop 0
	v_cndmask_b32_e32 v128, v167, v128, vcc
	v_lshlrev_b32_e32 v128, 2, v128
	ds_bpermute_b32 v128, v128, v140
	v_cmp_lt_i32_e32 vcc, v129, v182
	s_waitcnt lgkmcnt(0)
	v_max_f32_e32 v128, v128, v128
	v_cndmask_b32_e32 v129, v167, v129, vcc
	v_max_f32_e32 v128, v140, v128
	v_lshlrev_b32_e32 v129, 2, v129
	ds_bpermute_b32 v129, v129, v128
	s_waitcnt lgkmcnt(0)
	v_max_f32_e32 v129, v129, v129
	v_max_f32_e32 v128, v128, v129
	v_xor_b32_e32 v129, 4, v167
	v_cmp_lt_i32_e32 vcc, v129, v182
	s_nop 1
	v_cndmask_b32_e32 v129, v167, v129, vcc
	v_lshlrev_b32_e32 v129, 2, v129
	ds_bpermute_b32 v129, v129, v128
	s_waitcnt lgkmcnt(0)
	v_max_f32_e32 v129, v129, v129
	v_max_f32_e32 v128, v128, v129
	v_xor_b32_e32 v129, 8, v167
	v_cmp_lt_i32_e32 vcc, v129, v182
	s_nop 1
	v_cndmask_b32_e32 v129, v167, v129, vcc
	v_lshlrev_b32_e32 v129, 2, v129
	ds_bpermute_b32 v129, v129, v128
	s_and_saveexec_b64 s[2:3], s[4:5]
	s_cbranch_execz .LBB0_695
	s_waitcnt lgkmcnt(0)
	v_max_f32_e32 v129, v129, v129
	v_max_f32_e32 v128, v128, v128
	s_mov_b64 s[8:9], exec
	v_max_f32_e32 v128, v128, v129
	s_mov_b32 s28, 0
